# scan_final item body hand-written: 16 summaries / 16 rows of loads in flight instead of one round trip each
# speedup vs baseline: 1.0648x; 1.0405x over previous
.LBB0_1007:
	s_mul_hi_i32 s17, s16, 0x55555556
	s_lshr_b32 s2, s17, 31
	s_add_i32 s17, s17, s2
	s_waitcnt vmcnt(7)
	v_mov_b32_e32 v0, v192
	s_mul_i32 s2, s17, -3
	s_add_i32 s2, s2, s16
	v_lshlrev_b32_e32 v0, 1, v0
	v_lshl_add_u32 v0, s2, 9, v0
	s_movk_i32 s2, 0x500
	v_cmp_gt_i32_e32 vcc, s2, v0
	s_and_saveexec_b64 s[14:15], vcc
	s_cbranch_execz .LBB0_1006
	v_lshlrev_b32_e32 v2, 2, v0
	v_mov_b32_e32 v8, 0
	v_mov_b32_e32 v9, 0
	s_mov_b32 s18, 0
.Lsf_pfull:
	s_add_i32 s19, s18, 16
	s_cmp_le_u32 s19, s17
	s_cbranch_scc0 .Lsf_ptail
	global_load_dwordx2 v[44:45], v2, s[8:9]
	global_load_dwordx2 v[46:47], v2, s[10:11]
	v_add_u32_e32 v2, 0x1400, v2
	global_load_dwordx2 v[48:49], v2, s[8:9]
	global_load_dwordx2 v[50:51], v2, s[10:11]
	v_add_u32_e32 v2, 0x1400, v2
	global_load_dwordx2 v[52:53], v2, s[8:9]
	global_load_dwordx2 v[54:55], v2, s[10:11]
	v_add_u32_e32 v2, 0x1400, v2
	global_load_dwordx2 v[56:57], v2, s[8:9]
	global_load_dwordx2 v[58:59], v2, s[10:11]
	v_add_u32_e32 v2, 0x1400, v2
	global_load_dwordx2 v[60:61], v2, s[8:9]
	global_load_dwordx2 v[62:63], v2, s[10:11]
	v_add_u32_e32 v2, 0x1400, v2
	global_load_dwordx2 v[64:65], v2, s[8:9]
	global_load_dwordx2 v[66:67], v2, s[10:11]
	v_add_u32_e32 v2, 0x1400, v2
	global_load_dwordx2 v[68:69], v2, s[8:9]
	global_load_dwordx2 v[70:71], v2, s[10:11]
	v_add_u32_e32 v2, 0x1400, v2
	global_load_dwordx2 v[72:73], v2, s[8:9]
	global_load_dwordx2 v[74:75], v2, s[10:11]
	v_add_u32_e32 v2, 0x1400, v2
	global_load_dwordx2 v[76:77], v2, s[8:9]
	global_load_dwordx2 v[78:79], v2, s[10:11]
	v_add_u32_e32 v2, 0x1400, v2
	global_load_dwordx2 v[80:81], v2, s[8:9]
	global_load_dwordx2 v[82:83], v2, s[10:11]
	v_add_u32_e32 v2, 0x1400, v2
	global_load_dwordx2 v[84:85], v2, s[8:9]
	global_load_dwordx2 v[86:87], v2, s[10:11]
	v_add_u32_e32 v2, 0x1400, v2
	global_load_dwordx2 v[88:89], v2, s[8:9]
	global_load_dwordx2 v[90:91], v2, s[10:11]
	v_add_u32_e32 v2, 0x1400, v2
	global_load_dwordx2 v[92:93], v2, s[8:9]
	global_load_dwordx2 v[94:95], v2, s[10:11]
	v_add_u32_e32 v2, 0x1400, v2
	global_load_dwordx2 v[96:97], v2, s[8:9]
	global_load_dwordx2 v[98:99], v2, s[10:11]
	v_add_u32_e32 v2, 0x1400, v2
	global_load_dwordx2 v[100:101], v2, s[8:9]
	global_load_dwordx2 v[102:103], v2, s[10:11]
	v_add_u32_e32 v2, 0x1400, v2
	global_load_dwordx2 v[104:105], v2, s[8:9]
	global_load_dwordx2 v[106:107], v2, s[10:11]
	v_add_u32_e32 v2, 0x1400, v2
	s_waitcnt vmcnt(30)
	v_mul_f32_e32 v44, 0x3fb8aa3b, v44
	v_mul_f32_e32 v45, 0x3fb8aa3b, v45
	v_exp_f32_e32 v44, v44
	v_exp_f32_e32 v45, v45
	s_nop 1
	v_pk_fma_f32 v[8:9], v[8:9], v[44:45], v[46:47]
	s_waitcnt vmcnt(28)
	v_mul_f32_e32 v48, 0x3fb8aa3b, v48
	v_mul_f32_e32 v49, 0x3fb8aa3b, v49
	v_exp_f32_e32 v48, v48
	v_exp_f32_e32 v49, v49
	s_nop 1
	v_pk_fma_f32 v[8:9], v[8:9], v[48:49], v[50:51]
	s_waitcnt vmcnt(26)
	v_mul_f32_e32 v52, 0x3fb8aa3b, v52
	v_mul_f32_e32 v53, 0x3fb8aa3b, v53
	v_exp_f32_e32 v52, v52
	v_exp_f32_e32 v53, v53
	s_nop 1
	v_pk_fma_f32 v[8:9], v[8:9], v[52:53], v[54:55]
	s_waitcnt vmcnt(24)
	v_mul_f32_e32 v56, 0x3fb8aa3b, v56
	v_mul_f32_e32 v57, 0x3fb8aa3b, v57
	v_exp_f32_e32 v56, v56
	v_exp_f32_e32 v57, v57
	s_nop 1
	v_pk_fma_f32 v[8:9], v[8:9], v[56:57], v[58:59]
	s_waitcnt vmcnt(22)
	v_mul_f32_e32 v60, 0x3fb8aa3b, v60
	v_mul_f32_e32 v61, 0x3fb8aa3b, v61
	v_exp_f32_e32 v60, v60
	v_exp_f32_e32 v61, v61
	s_nop 1
	v_pk_fma_f32 v[8:9], v[8:9], v[60:61], v[62:63]
	s_waitcnt vmcnt(20)
	v_mul_f32_e32 v64, 0x3fb8aa3b, v64
	v_mul_f32_e32 v65, 0x3fb8aa3b, v65
	v_exp_f32_e32 v64, v64
	v_exp_f32_e32 v65, v65
	s_nop 1
	v_pk_fma_f32 v[8:9], v[8:9], v[64:65], v[66:67]
	s_waitcnt vmcnt(18)
	v_mul_f32_e32 v68, 0x3fb8aa3b, v68
	v_mul_f32_e32 v69, 0x3fb8aa3b, v69
	v_exp_f32_e32 v68, v68
	v_exp_f32_e32 v69, v69
	s_nop 1
	v_pk_fma_f32 v[8:9], v[8:9], v[68:69], v[70:71]
	s_waitcnt vmcnt(16)
	v_mul_f32_e32 v72, 0x3fb8aa3b, v72
	v_mul_f32_e32 v73, 0x3fb8aa3b, v73
	v_exp_f32_e32 v72, v72
	v_exp_f32_e32 v73, v73
	s_nop 1
	v_pk_fma_f32 v[8:9], v[8:9], v[72:73], v[74:75]
	s_waitcnt vmcnt(14)
	v_mul_f32_e32 v76, 0x3fb8aa3b, v76
	v_mul_f32_e32 v77, 0x3fb8aa3b, v77
	v_exp_f32_e32 v76, v76
	v_exp_f32_e32 v77, v77
	s_nop 1
	v_pk_fma_f32 v[8:9], v[8:9], v[76:77], v[78:79]
	s_waitcnt vmcnt(12)
	v_mul_f32_e32 v80, 0x3fb8aa3b, v80
	v_mul_f32_e32 v81, 0x3fb8aa3b, v81
	v_exp_f32_e32 v80, v80
	v_exp_f32_e32 v81, v81
	s_nop 1
	v_pk_fma_f32 v[8:9], v[8:9], v[80:81], v[82:83]
	s_waitcnt vmcnt(10)
	v_mul_f32_e32 v84, 0x3fb8aa3b, v84
	v_mul_f32_e32 v85, 0x3fb8aa3b, v85
	v_exp_f32_e32 v84, v84
	v_exp_f32_e32 v85, v85
	s_nop 1
	v_pk_fma_f32 v[8:9], v[8:9], v[84:85], v[86:87]
	s_waitcnt vmcnt(8)
	v_mul_f32_e32 v88, 0x3fb8aa3b, v88
	v_mul_f32_e32 v89, 0x3fb8aa3b, v89
	v_exp_f32_e32 v88, v88
	v_exp_f32_e32 v89, v89
	s_nop 1
	v_pk_fma_f32 v[8:9], v[8:9], v[88:89], v[90:91]
	s_waitcnt vmcnt(6)
	v_mul_f32_e32 v92, 0x3fb8aa3b, v92
	v_mul_f32_e32 v93, 0x3fb8aa3b, v93
	v_exp_f32_e32 v92, v92
	v_exp_f32_e32 v93, v93
	s_nop 1
	v_pk_fma_f32 v[8:9], v[8:9], v[92:93], v[94:95]
	s_waitcnt vmcnt(4)
	v_mul_f32_e32 v96, 0x3fb8aa3b, v96
	v_mul_f32_e32 v97, 0x3fb8aa3b, v97
	v_exp_f32_e32 v96, v96
	v_exp_f32_e32 v97, v97
	s_nop 1
	v_pk_fma_f32 v[8:9], v[8:9], v[96:97], v[98:99]
	s_waitcnt vmcnt(2)
	v_mul_f32_e32 v100, 0x3fb8aa3b, v100
	v_mul_f32_e32 v101, 0x3fb8aa3b, v101
	v_exp_f32_e32 v100, v100
	v_exp_f32_e32 v101, v101
	s_nop 1
	v_pk_fma_f32 v[8:9], v[8:9], v[100:101], v[102:103]
	s_waitcnt vmcnt(0)
	v_mul_f32_e32 v104, 0x3fb8aa3b, v104
	v_mul_f32_e32 v105, 0x3fb8aa3b, v105
	v_exp_f32_e32 v104, v104
	v_exp_f32_e32 v105, v105
	s_nop 1
	v_pk_fma_f32 v[8:9], v[8:9], v[104:105], v[106:107]
	s_mov_b32 s18, s19
	s_branch .Lsf_pfull
.Lsf_ptail:
	s_cmp_lt_u32 s18, s17
	s_cbranch_scc0 .Lsf_rows
	global_load_dwordx2 v[44:45], v2, s[8:9]
	global_load_dwordx2 v[46:47], v2, s[10:11]
	s_add_i32 s19, s18, 1
	s_cmp_lt_u32 s19, s17
	s_cselect_b32 s19, 0x1400, 0
	v_add_u32_e32 v2, s19, v2
	global_load_dwordx2 v[48:49], v2, s[8:9]
	global_load_dwordx2 v[50:51], v2, s[10:11]
	s_add_i32 s19, s18, 2
	s_cmp_lt_u32 s19, s17
	s_cselect_b32 s19, 0x1400, 0
	v_add_u32_e32 v2, s19, v2
	global_load_dwordx2 v[52:53], v2, s[8:9]
	global_load_dwordx2 v[54:55], v2, s[10:11]
	s_add_i32 s19, s18, 3
	s_cmp_lt_u32 s19, s17
	s_cselect_b32 s19, 0x1400, 0
	v_add_u32_e32 v2, s19, v2
	global_load_dwordx2 v[56:57], v2, s[8:9]
	global_load_dwordx2 v[58:59], v2, s[10:11]
	s_add_i32 s19, s18, 4
	s_cmp_lt_u32 s19, s17
	s_cselect_b32 s19, 0x1400, 0
	v_add_u32_e32 v2, s19, v2
	global_load_dwordx2 v[60:61], v2, s[8:9]
	global_load_dwordx2 v[62:63], v2, s[10:11]
	s_add_i32 s19, s18, 5
	s_cmp_lt_u32 s19, s17
	s_cselect_b32 s19, 0x1400, 0
	v_add_u32_e32 v2, s19, v2
	global_load_dwordx2 v[64:65], v2, s[8:9]
	global_load_dwordx2 v[66:67], v2, s[10:11]
	s_add_i32 s19, s18, 6
	s_cmp_lt_u32 s19, s17
	s_cselect_b32 s19, 0x1400, 0
	v_add_u32_e32 v2, s19, v2
	global_load_dwordx2 v[68:69], v2, s[8:9]
	global_load_dwordx2 v[70:71], v2, s[10:11]
	s_add_i32 s19, s18, 7
	s_cmp_lt_u32 s19, s17
	s_cselect_b32 s19, 0x1400, 0
	v_add_u32_e32 v2, s19, v2
	global_load_dwordx2 v[72:73], v2, s[8:9]
	global_load_dwordx2 v[74:75], v2, s[10:11]
	s_add_i32 s19, s18, 8
	s_cmp_lt_u32 s19, s17
	s_cselect_b32 s19, 0x1400, 0
	v_add_u32_e32 v2, s19, v2
	global_load_dwordx2 v[76:77], v2, s[8:9]
	global_load_dwordx2 v[78:79], v2, s[10:11]
	s_add_i32 s19, s18, 9
	s_cmp_lt_u32 s19, s17
	s_cselect_b32 s19, 0x1400, 0
	v_add_u32_e32 v2, s19, v2
	global_load_dwordx2 v[80:81], v2, s[8:9]
	global_load_dwordx2 v[82:83], v2, s[10:11]
	s_add_i32 s19, s18, 10
	s_cmp_lt_u32 s19, s17
	s_cselect_b32 s19, 0x1400, 0
	v_add_u32_e32 v2, s19, v2
	global_load_dwordx2 v[84:85], v2, s[8:9]
	global_load_dwordx2 v[86:87], v2, s[10:11]
	s_add_i32 s19, s18, 11
	s_cmp_lt_u32 s19, s17
	s_cselect_b32 s19, 0x1400, 0
	v_add_u32_e32 v2, s19, v2
	global_load_dwordx2 v[88:89], v2, s[8:9]
	global_load_dwordx2 v[90:91], v2, s[10:11]
	s_add_i32 s19, s18, 12
	s_cmp_lt_u32 s19, s17
	s_cselect_b32 s19, 0x1400, 0
	v_add_u32_e32 v2, s19, v2
	global_load_dwordx2 v[92:93], v2, s[8:9]
	global_load_dwordx2 v[94:95], v2, s[10:11]
	s_add_i32 s19, s18, 13
	s_cmp_lt_u32 s19, s17
	s_cselect_b32 s19, 0x1400, 0
	v_add_u32_e32 v2, s19, v2
	global_load_dwordx2 v[96:97], v2, s[8:9]
	global_load_dwordx2 v[98:99], v2, s[10:11]
	s_add_i32 s19, s18, 14
	s_cmp_lt_u32 s19, s17
	s_cselect_b32 s19, 0x1400, 0
	v_add_u32_e32 v2, s19, v2
	global_load_dwordx2 v[100:101], v2, s[8:9]
	global_load_dwordx2 v[102:103], v2, s[10:11]
	s_add_i32 s19, s18, 15
	s_cmp_lt_u32 s19, s17
	s_cselect_b32 s19, 0x1400, 0
	v_add_u32_e32 v2, s19, v2
	s_waitcnt vmcnt(0)
	s_add_i32 s19, s18, 0
	s_cmp_lt_u32 s19, s17
	s_cselect_b64 s[2:3], -1, 0
	v_mul_f32_e32 v44, 0x3fb8aa3b, v44
	v_mul_f32_e32 v45, 0x3fb8aa3b, v45
	v_exp_f32_e32 v44, v44
	v_exp_f32_e32 v45, v45
	s_nop 1
	v_cndmask_b32_e64 v44, 1.0, v44, s[2:3]
	v_cndmask_b32_e64 v45, 1.0, v45, s[2:3]
	v_cndmask_b32_e64 v46, 0, v46, s[2:3]
	v_cndmask_b32_e64 v47, 0, v47, s[2:3]
	v_pk_fma_f32 v[8:9], v[8:9], v[44:45], v[46:47]
	s_add_i32 s19, s18, 1
	s_cmp_lt_u32 s19, s17
	s_cselect_b64 s[2:3], -1, 0
	v_mul_f32_e32 v48, 0x3fb8aa3b, v48
	v_mul_f32_e32 v49, 0x3fb8aa3b, v49
	v_exp_f32_e32 v48, v48
	v_exp_f32_e32 v49, v49
	s_nop 1
	v_cndmask_b32_e64 v48, 1.0, v48, s[2:3]
	v_cndmask_b32_e64 v49, 1.0, v49, s[2:3]
	v_cndmask_b32_e64 v50, 0, v50, s[2:3]
	v_cndmask_b32_e64 v51, 0, v51, s[2:3]
	v_pk_fma_f32 v[8:9], v[8:9], v[48:49], v[50:51]
	s_add_i32 s19, s18, 2
	s_cmp_lt_u32 s19, s17
	s_cselect_b64 s[2:3], -1, 0
	v_mul_f32_e32 v52, 0x3fb8aa3b, v52
	v_mul_f32_e32 v53, 0x3fb8aa3b, v53
	v_exp_f32_e32 v52, v52
	v_exp_f32_e32 v53, v53
	s_nop 1
	v_cndmask_b32_e64 v52, 1.0, v52, s[2:3]
	v_cndmask_b32_e64 v53, 1.0, v53, s[2:3]
	v_cndmask_b32_e64 v54, 0, v54, s[2:3]
	v_cndmask_b32_e64 v55, 0, v55, s[2:3]
	v_pk_fma_f32 v[8:9], v[8:9], v[52:53], v[54:55]
	s_add_i32 s19, s18, 3
	s_cmp_lt_u32 s19, s17
	s_cselect_b64 s[2:3], -1, 0
	v_mul_f32_e32 v56, 0x3fb8aa3b, v56
	v_mul_f32_e32 v57, 0x3fb8aa3b, v57
	v_exp_f32_e32 v56, v56
	v_exp_f32_e32 v57, v57
	s_nop 1
	v_cndmask_b32_e64 v56, 1.0, v56, s[2:3]
	v_cndmask_b32_e64 v57, 1.0, v57, s[2:3]
	v_cndmask_b32_e64 v58, 0, v58, s[2:3]
	v_cndmask_b32_e64 v59, 0, v59, s[2:3]
	v_pk_fma_f32 v[8:9], v[8:9], v[56:57], v[58:59]
	s_add_i32 s19, s18, 4
	s_cmp_lt_u32 s19, s17
	s_cselect_b64 s[2:3], -1, 0
	v_mul_f32_e32 v60, 0x3fb8aa3b, v60
	v_mul_f32_e32 v61, 0x3fb8aa3b, v61
	v_exp_f32_e32 v60, v60
	v_exp_f32_e32 v61, v61
	s_nop 1
	v_cndmask_b32_e64 v60, 1.0, v60, s[2:3]
	v_cndmask_b32_e64 v61, 1.0, v61, s[2:3]
	v_cndmask_b32_e64 v62, 0, v62, s[2:3]
	v_cndmask_b32_e64 v63, 0, v63, s[2:3]
	v_pk_fma_f32 v[8:9], v[8:9], v[60:61], v[62:63]
	s_add_i32 s19, s18, 5
	s_cmp_lt_u32 s19, s17
	s_cselect_b64 s[2:3], -1, 0
	v_mul_f32_e32 v64, 0x3fb8aa3b, v64
	v_mul_f32_e32 v65, 0x3fb8aa3b, v65
	v_exp_f32_e32 v64, v64
	v_exp_f32_e32 v65, v65
	s_nop 1
	v_cndmask_b32_e64 v64, 1.0, v64, s[2:3]
	v_cndmask_b32_e64 v65, 1.0, v65, s[2:3]
	v_cndmask_b32_e64 v66, 0, v66, s[2:3]
	v_cndmask_b32_e64 v67, 0, v67, s[2:3]
	v_pk_fma_f32 v[8:9], v[8:9], v[64:65], v[66:67]
	s_add_i32 s19, s18, 6
	s_cmp_lt_u32 s19, s17
	s_cselect_b64 s[2:3], -1, 0
	v_mul_f32_e32 v68, 0x3fb8aa3b, v68
	v_mul_f32_e32 v69, 0x3fb8aa3b, v69
	v_exp_f32_e32 v68, v68
	v_exp_f32_e32 v69, v69
	s_nop 1
	v_cndmask_b32_e64 v68, 1.0, v68, s[2:3]
	v_cndmask_b32_e64 v69, 1.0, v69, s[2:3]
	v_cndmask_b32_e64 v70, 0, v70, s[2:3]
	v_cndmask_b32_e64 v71, 0, v71, s[2:3]
	v_pk_fma_f32 v[8:9], v[8:9], v[68:69], v[70:71]
	s_add_i32 s19, s18, 7
	s_cmp_lt_u32 s19, s17
	s_cselect_b64 s[2:3], -1, 0
	v_mul_f32_e32 v72, 0x3fb8aa3b, v72
	v_mul_f32_e32 v73, 0x3fb8aa3b, v73
	v_exp_f32_e32 v72, v72
	v_exp_f32_e32 v73, v73
	s_nop 1
	v_cndmask_b32_e64 v72, 1.0, v72, s[2:3]
	v_cndmask_b32_e64 v73, 1.0, v73, s[2:3]
	v_cndmask_b32_e64 v74, 0, v74, s[2:3]
	v_cndmask_b32_e64 v75, 0, v75, s[2:3]
	v_pk_fma_f32 v[8:9], v[8:9], v[72:73], v[74:75]
	s_add_i32 s19, s18, 8
	s_cmp_lt_u32 s19, s17
	s_cselect_b64 s[2:3], -1, 0
	v_mul_f32_e32 v76, 0x3fb8aa3b, v76
	v_mul_f32_e32 v77, 0x3fb8aa3b, v77
	v_exp_f32_e32 v76, v76
	v_exp_f32_e32 v77, v77
	s_nop 1
	v_cndmask_b32_e64 v76, 1.0, v76, s[2:3]
	v_cndmask_b32_e64 v77, 1.0, v77, s[2:3]
	v_cndmask_b32_e64 v78, 0, v78, s[2:3]
	v_cndmask_b32_e64 v79, 0, v79, s[2:3]
	v_pk_fma_f32 v[8:9], v[8:9], v[76:77], v[78:79]
	s_add_i32 s19, s18, 9
	s_cmp_lt_u32 s19, s17
	s_cselect_b64 s[2:3], -1, 0
	v_mul_f32_e32 v80, 0x3fb8aa3b, v80
	v_mul_f32_e32 v81, 0x3fb8aa3b, v81
	v_exp_f32_e32 v80, v80
	v_exp_f32_e32 v81, v81
	s_nop 1
	v_cndmask_b32_e64 v80, 1.0, v80, s[2:3]
	v_cndmask_b32_e64 v81, 1.0, v81, s[2:3]
	v_cndmask_b32_e64 v82, 0, v82, s[2:3]
	v_cndmask_b32_e64 v83, 0, v83, s[2:3]
	v_pk_fma_f32 v[8:9], v[8:9], v[80:81], v[82:83]
	s_add_i32 s19, s18, 10
	s_cmp_lt_u32 s19, s17
	s_cselect_b64 s[2:3], -1, 0
	v_mul_f32_e32 v84, 0x3fb8aa3b, v84
	v_mul_f32_e32 v85, 0x3fb8aa3b, v85
	v_exp_f32_e32 v84, v84
	v_exp_f32_e32 v85, v85
	s_nop 1
	v_cndmask_b32_e64 v84, 1.0, v84, s[2:3]
	v_cndmask_b32_e64 v85, 1.0, v85, s[2:3]
	v_cndmask_b32_e64 v86, 0, v86, s[2:3]
	v_cndmask_b32_e64 v87, 0, v87, s[2:3]
	v_pk_fma_f32 v[8:9], v[8:9], v[84:85], v[86:87]
	s_add_i32 s19, s18, 11
	s_cmp_lt_u32 s19, s17
	s_cselect_b64 s[2:3], -1, 0
	v_mul_f32_e32 v88, 0x3fb8aa3b, v88
	v_mul_f32_e32 v89, 0x3fb8aa3b, v89
	v_exp_f32_e32 v88, v88
	v_exp_f32_e32 v89, v89
	s_nop 1
	v_cndmask_b32_e64 v88, 1.0, v88, s[2:3]
	v_cndmask_b32_e64 v89, 1.0, v89, s[2:3]
	v_cndmask_b32_e64 v90, 0, v90, s[2:3]
	v_cndmask_b32_e64 v91, 0, v91, s[2:3]
	v_pk_fma_f32 v[8:9], v[8:9], v[88:89], v[90:91]
	s_add_i32 s19, s18, 12
	s_cmp_lt_u32 s19, s17
	s_cselect_b64 s[2:3], -1, 0
	v_mul_f32_e32 v92, 0x3fb8aa3b, v92
	v_mul_f32_e32 v93, 0x3fb8aa3b, v93
	v_exp_f32_e32 v92, v92
	v_exp_f32_e32 v93, v93
	s_nop 1
	v_cndmask_b32_e64 v92, 1.0, v92, s[2:3]
	v_cndmask_b32_e64 v93, 1.0, v93, s[2:3]
	v_cndmask_b32_e64 v94, 0, v94, s[2:3]
	v_cndmask_b32_e64 v95, 0, v95, s[2:3]
	v_pk_fma_f32 v[8:9], v[8:9], v[92:93], v[94:95]
	s_add_i32 s19, s18, 13
	s_cmp_lt_u32 s19, s17
	s_cselect_b64 s[2:3], -1, 0
	v_mul_f32_e32 v96, 0x3fb8aa3b, v96
	v_mul_f32_e32 v97, 0x3fb8aa3b, v97
	v_exp_f32_e32 v96, v96
	v_exp_f32_e32 v97, v97
	s_nop 1
	v_cndmask_b32_e64 v96, 1.0, v96, s[2:3]
	v_cndmask_b32_e64 v97, 1.0, v97, s[2:3]
	v_cndmask_b32_e64 v98, 0, v98, s[2:3]
	v_cndmask_b32_e64 v99, 0, v99, s[2:3]
	v_pk_fma_f32 v[8:9], v[8:9], v[96:97], v[98:99]
	s_add_i32 s19, s18, 14
	s_cmp_lt_u32 s19, s17
	s_cselect_b64 s[2:3], -1, 0
	v_mul_f32_e32 v100, 0x3fb8aa3b, v100
	v_mul_f32_e32 v101, 0x3fb8aa3b, v101
	v_exp_f32_e32 v100, v100
	v_exp_f32_e32 v101, v101
	s_nop 1
	v_cndmask_b32_e64 v100, 1.0, v100, s[2:3]
	v_cndmask_b32_e64 v101, 1.0, v101, s[2:3]
	v_cndmask_b32_e64 v102, 0, v102, s[2:3]
	v_cndmask_b32_e64 v103, 0, v103, s[2:3]
	v_pk_fma_f32 v[8:9], v[8:9], v[100:101], v[102:103]
.Lsf_rows:
	s_lshl_b32 s2, s17, 6
	s_sub_i32 s3, 0x4020, s2
	s_min_u32 s3, s3, 64
	s_mul_i32 s2, s17, 0x28000
	s_add_u32 s18, s0, s2
	s_addc_u32 s19, s1, 0
	s_add_u32 s20, s4, s2
	s_addc_u32 s21, s5, 0
	s_add_u32 s22, s6, s2
	s_addc_u32 s23, s7, 0
	v_lshlrev_b32_e32 v3, 1, v0
	v_mov_b32_e32 v4, v3
	global_load_dword v108, v3, s[18:19]
	global_load_dword v124, v3, s[20:21]
	global_load_dword v140, v3, s[22:23]
	v_add_u32_e32 v3, 0xa00, v3
	global_load_dword v109, v3, s[18:19]
	global_load_dword v125, v3, s[20:21]
	global_load_dword v141, v3, s[22:23]
	v_add_u32_e32 v3, 0xa00, v3
	global_load_dword v110, v3, s[18:19]
	global_load_dword v126, v3, s[20:21]
	global_load_dword v142, v3, s[22:23]
	v_add_u32_e32 v3, 0xa00, v3
	global_load_dword v111, v3, s[18:19]
	global_load_dword v127, v3, s[20:21]
	global_load_dword v143, v3, s[22:23]
	v_add_u32_e32 v3, 0xa00, v3
	global_load_dword v112, v3, s[18:19]
	global_load_dword v128, v3, s[20:21]
	global_load_dword v144, v3, s[22:23]
	v_add_u32_e32 v3, 0xa00, v3
	global_load_dword v113, v3, s[18:19]
	global_load_dword v129, v3, s[20:21]
	global_load_dword v145, v3, s[22:23]
	v_add_u32_e32 v3, 0xa00, v3
	global_load_dword v114, v3, s[18:19]
	global_load_dword v130, v3, s[20:21]
	global_load_dword v146, v3, s[22:23]
	v_add_u32_e32 v3, 0xa00, v3
	global_load_dword v115, v3, s[18:19]
	global_load_dword v131, v3, s[20:21]
	global_load_dword v147, v3, s[22:23]
	v_add_u32_e32 v3, 0xa00, v3
	global_load_dword v116, v3, s[18:19]
	global_load_dword v132, v3, s[20:21]
	global_load_dword v148, v3, s[22:23]
	v_add_u32_e32 v3, 0xa00, v3
	global_load_dword v117, v3, s[18:19]
	global_load_dword v133, v3, s[20:21]
	global_load_dword v149, v3, s[22:23]
	v_add_u32_e32 v3, 0xa00, v3
	global_load_dword v118, v3, s[18:19]
	global_load_dword v134, v3, s[20:21]
	global_load_dword v150, v3, s[22:23]
	v_add_u32_e32 v3, 0xa00, v3
	global_load_dword v119, v3, s[18:19]
	global_load_dword v135, v3, s[20:21]
	global_load_dword v151, v3, s[22:23]
	v_add_u32_e32 v3, 0xa00, v3
	global_load_dword v120, v3, s[18:19]
	global_load_dword v136, v3, s[20:21]
	global_load_dword v152, v3, s[22:23]
	v_add_u32_e32 v3, 0xa00, v3
	global_load_dword v121, v3, s[18:19]
	global_load_dword v137, v3, s[20:21]
	global_load_dword v153, v3, s[22:23]
	v_add_u32_e32 v3, 0xa00, v3
	global_load_dword v122, v3, s[18:19]
	global_load_dword v138, v3, s[20:21]
	global_load_dword v154, v3, s[22:23]
	v_add_u32_e32 v3, 0xa00, v3
	global_load_dword v123, v3, s[18:19]
	global_load_dword v139, v3, s[20:21]
	global_load_dword v155, v3, s[22:23]
	v_add_u32_e32 v3, 0xa00, v3
	s_waitcnt vmcnt(0)
	global_load_dword v44, v3, s[18:19]
	global_load_dword v60, v3, s[20:21]
	global_load_dword v76, v3, s[22:23]
	v_add_u32_e32 v3, 0xa00, v3
	global_load_dword v45, v3, s[18:19]
	global_load_dword v61, v3, s[20:21]
	global_load_dword v77, v3, s[22:23]
	v_add_u32_e32 v3, 0xa00, v3
	global_load_dword v46, v3, s[18:19]
	global_load_dword v62, v3, s[20:21]
	global_load_dword v78, v3, s[22:23]
	v_add_u32_e32 v3, 0xa00, v3
	global_load_dword v47, v3, s[18:19]
	global_load_dword v63, v3, s[20:21]
	global_load_dword v79, v3, s[22:23]
	v_add_u32_e32 v3, 0xa00, v3
	global_load_dword v48, v3, s[18:19]
	global_load_dword v64, v3, s[20:21]
	global_load_dword v80, v3, s[22:23]
	v_add_u32_e32 v3, 0xa00, v3
	global_load_dword v49, v3, s[18:19]
	global_load_dword v65, v3, s[20:21]
	global_load_dword v81, v3, s[22:23]
	v_add_u32_e32 v3, 0xa00, v3
	global_load_dword v50, v3, s[18:19]
	global_load_dword v66, v3, s[20:21]
	global_load_dword v82, v3, s[22:23]
	v_add_u32_e32 v3, 0xa00, v3
	global_load_dword v51, v3, s[18:19]
	global_load_dword v67, v3, s[20:21]
	global_load_dword v83, v3, s[22:23]
	v_add_u32_e32 v3, 0xa00, v3
	global_load_dword v52, v3, s[18:19]
	global_load_dword v68, v3, s[20:21]
	global_load_dword v84, v3, s[22:23]
	v_add_u32_e32 v3, 0xa00, v3
	global_load_dword v53, v3, s[18:19]
	global_load_dword v69, v3, s[20:21]
	global_load_dword v85, v3, s[22:23]
	v_add_u32_e32 v3, 0xa00, v3
	global_load_dword v54, v3, s[18:19]
	global_load_dword v70, v3, s[20:21]
	global_load_dword v86, v3, s[22:23]
	v_add_u32_e32 v3, 0xa00, v3
	global_load_dword v55, v3, s[18:19]
	global_load_dword v71, v3, s[20:21]
	global_load_dword v87, v3, s[22:23]
	v_add_u32_e32 v3, 0xa00, v3
	global_load_dword v56, v3, s[18:19]
	global_load_dword v72, v3, s[20:21]
	global_load_dword v88, v3, s[22:23]
	v_add_u32_e32 v3, 0xa00, v3
	global_load_dword v57, v3, s[18:19]
	global_load_dword v73, v3, s[20:21]
	global_load_dword v89, v3, s[22:23]
	v_add_u32_e32 v3, 0xa00, v3
	global_load_dword v58, v3, s[18:19]
	global_load_dword v74, v3, s[20:21]
	global_load_dword v90, v3, s[22:23]
	v_add_u32_e32 v3, 0xa00, v3
	global_load_dword v59, v3, s[18:19]
	global_load_dword v75, v3, s[20:21]
	global_load_dword v91, v3, s[22:23]
	v_add_u32_e32 v3, 0xa00, v3
	v_lshlrev_b32_e32 v10, 16, v108
	v_and_b32_e32 v11, 0xffff0000, v108
	v_mul_f32_e32 v10, 0x3fb8aa3b, v10
	v_mul_f32_e32 v11, 0x3fb8aa3b, v11
	v_exp_f32_e32 v10, v10
	v_exp_f32_e32 v11, v11
	v_lshlrev_b32_e32 v12, 16, v124
	v_and_b32_e32 v13, 0xffff0000, v124
	v_pk_fma_f32 v[8:9], v[8:9], v[10:11], v[12:13]
	v_lshlrev_b32_e32 v14, 16, v140
	v_and_b32_e32 v15, 0xffff0000, v140
	v_mul_f32_e32 v14, v8, v14
	v_mul_f32_e32 v15, v9, v15
	v_cvt_pk_bf16_f32 v14, v14, v15
	global_store_dword v4, v14, s[22:23]
	v_add_u32_e32 v4, 0xa00, v4
	v_lshlrev_b32_e32 v10, 16, v109
	v_and_b32_e32 v11, 0xffff0000, v109
	v_mul_f32_e32 v10, 0x3fb8aa3b, v10
	v_mul_f32_e32 v11, 0x3fb8aa3b, v11
	v_exp_f32_e32 v10, v10
	v_exp_f32_e32 v11, v11
	v_lshlrev_b32_e32 v12, 16, v125
	v_and_b32_e32 v13, 0xffff0000, v125
	v_pk_fma_f32 v[8:9], v[8:9], v[10:11], v[12:13]
	v_lshlrev_b32_e32 v14, 16, v141
	v_and_b32_e32 v15, 0xffff0000, v141
	v_mul_f32_e32 v14, v8, v14
	v_mul_f32_e32 v15, v9, v15
	v_cvt_pk_bf16_f32 v14, v14, v15
	global_store_dword v4, v14, s[22:23]
	v_add_u32_e32 v4, 0xa00, v4
	v_lshlrev_b32_e32 v10, 16, v110
	v_and_b32_e32 v11, 0xffff0000, v110
	v_mul_f32_e32 v10, 0x3fb8aa3b, v10
	v_mul_f32_e32 v11, 0x3fb8aa3b, v11
	v_exp_f32_e32 v10, v10
	v_exp_f32_e32 v11, v11
	v_lshlrev_b32_e32 v12, 16, v126
	v_and_b32_e32 v13, 0xffff0000, v126
	v_pk_fma_f32 v[8:9], v[8:9], v[10:11], v[12:13]
	v_lshlrev_b32_e32 v14, 16, v142
	v_and_b32_e32 v15, 0xffff0000, v142
	v_mul_f32_e32 v14, v8, v14
	v_mul_f32_e32 v15, v9, v15
	v_cvt_pk_bf16_f32 v14, v14, v15
	global_store_dword v4, v14, s[22:23]
	v_add_u32_e32 v4, 0xa00, v4
	v_lshlrev_b32_e32 v10, 16, v111
	v_and_b32_e32 v11, 0xffff0000, v111
	v_mul_f32_e32 v10, 0x3fb8aa3b, v10
	v_mul_f32_e32 v11, 0x3fb8aa3b, v11
	v_exp_f32_e32 v10, v10
	v_exp_f32_e32 v11, v11
	v_lshlrev_b32_e32 v12, 16, v127
	v_and_b32_e32 v13, 0xffff0000, v127
	v_pk_fma_f32 v[8:9], v[8:9], v[10:11], v[12:13]
	v_lshlrev_b32_e32 v14, 16, v143
	v_and_b32_e32 v15, 0xffff0000, v143
	v_mul_f32_e32 v14, v8, v14
	v_mul_f32_e32 v15, v9, v15
	v_cvt_pk_bf16_f32 v14, v14, v15
	global_store_dword v4, v14, s[22:23]
	v_add_u32_e32 v4, 0xa00, v4
	v_lshlrev_b32_e32 v10, 16, v112
	v_and_b32_e32 v11, 0xffff0000, v112
	v_mul_f32_e32 v10, 0x3fb8aa3b, v10
	v_mul_f32_e32 v11, 0x3fb8aa3b, v11
	v_exp_f32_e32 v10, v10
	v_exp_f32_e32 v11, v11
	v_lshlrev_b32_e32 v12, 16, v128
	v_and_b32_e32 v13, 0xffff0000, v128
	v_pk_fma_f32 v[8:9], v[8:9], v[10:11], v[12:13]
	v_lshlrev_b32_e32 v14, 16, v144
	v_and_b32_e32 v15, 0xffff0000, v144
	v_mul_f32_e32 v14, v8, v14
	v_mul_f32_e32 v15, v9, v15
	v_cvt_pk_bf16_f32 v14, v14, v15
	global_store_dword v4, v14, s[22:23]
	v_add_u32_e32 v4, 0xa00, v4
	v_lshlrev_b32_e32 v10, 16, v113
	v_and_b32_e32 v11, 0xffff0000, v113
	v_mul_f32_e32 v10, 0x3fb8aa3b, v10
	v_mul_f32_e32 v11, 0x3fb8aa3b, v11
	v_exp_f32_e32 v10, v10
	v_exp_f32_e32 v11, v11
	v_lshlrev_b32_e32 v12, 16, v129
	v_and_b32_e32 v13, 0xffff0000, v129
	v_pk_fma_f32 v[8:9], v[8:9], v[10:11], v[12:13]
	v_lshlrev_b32_e32 v14, 16, v145
	v_and_b32_e32 v15, 0xffff0000, v145
	v_mul_f32_e32 v14, v8, v14
	v_mul_f32_e32 v15, v9, v15
	v_cvt_pk_bf16_f32 v14, v14, v15
	global_store_dword v4, v14, s[22:23]
	v_add_u32_e32 v4, 0xa00, v4
	v_lshlrev_b32_e32 v10, 16, v114
	v_and_b32_e32 v11, 0xffff0000, v114
	v_mul_f32_e32 v10, 0x3fb8aa3b, v10
	v_mul_f32_e32 v11, 0x3fb8aa3b, v11
	v_exp_f32_e32 v10, v10
	v_exp_f32_e32 v11, v11
	v_lshlrev_b32_e32 v12, 16, v130
	v_and_b32_e32 v13, 0xffff0000, v130
	v_pk_fma_f32 v[8:9], v[8:9], v[10:11], v[12:13]
	v_lshlrev_b32_e32 v14, 16, v146
	v_and_b32_e32 v15, 0xffff0000, v146
	v_mul_f32_e32 v14, v8, v14
	v_mul_f32_e32 v15, v9, v15
	v_cvt_pk_bf16_f32 v14, v14, v15
	global_store_dword v4, v14, s[22:23]
	v_add_u32_e32 v4, 0xa00, v4
	v_lshlrev_b32_e32 v10, 16, v115
	v_and_b32_e32 v11, 0xffff0000, v115
	v_mul_f32_e32 v10, 0x3fb8aa3b, v10
	v_mul_f32_e32 v11, 0x3fb8aa3b, v11
	v_exp_f32_e32 v10, v10
	v_exp_f32_e32 v11, v11
	v_lshlrev_b32_e32 v12, 16, v131
	v_and_b32_e32 v13, 0xffff0000, v131
	v_pk_fma_f32 v[8:9], v[8:9], v[10:11], v[12:13]
	v_lshlrev_b32_e32 v14, 16, v147
	v_and_b32_e32 v15, 0xffff0000, v147
	v_mul_f32_e32 v14, v8, v14
	v_mul_f32_e32 v15, v9, v15
	v_cvt_pk_bf16_f32 v14, v14, v15
	global_store_dword v4, v14, s[22:23]
	v_add_u32_e32 v4, 0xa00, v4
	v_lshlrev_b32_e32 v10, 16, v116
	v_and_b32_e32 v11, 0xffff0000, v116
	v_mul_f32_e32 v10, 0x3fb8aa3b, v10
	v_mul_f32_e32 v11, 0x3fb8aa3b, v11
	v_exp_f32_e32 v10, v10
	v_exp_f32_e32 v11, v11
	v_lshlrev_b32_e32 v12, 16, v132
	v_and_b32_e32 v13, 0xffff0000, v132
	v_pk_fma_f32 v[8:9], v[8:9], v[10:11], v[12:13]
	v_lshlrev_b32_e32 v14, 16, v148
	v_and_b32_e32 v15, 0xffff0000, v148
	v_mul_f32_e32 v14, v8, v14
	v_mul_f32_e32 v15, v9, v15
	v_cvt_pk_bf16_f32 v14, v14, v15
	global_store_dword v4, v14, s[22:23]
	v_add_u32_e32 v4, 0xa00, v4
	v_lshlrev_b32_e32 v10, 16, v117
	v_and_b32_e32 v11, 0xffff0000, v117
	v_mul_f32_e32 v10, 0x3fb8aa3b, v10
	v_mul_f32_e32 v11, 0x3fb8aa3b, v11
	v_exp_f32_e32 v10, v10
	v_exp_f32_e32 v11, v11
	v_lshlrev_b32_e32 v12, 16, v133
	v_and_b32_e32 v13, 0xffff0000, v133
	v_pk_fma_f32 v[8:9], v[8:9], v[10:11], v[12:13]
	v_lshlrev_b32_e32 v14, 16, v149
	v_and_b32_e32 v15, 0xffff0000, v149
	v_mul_f32_e32 v14, v8, v14
	v_mul_f32_e32 v15, v9, v15
	v_cvt_pk_bf16_f32 v14, v14, v15
	global_store_dword v4, v14, s[22:23]
	v_add_u32_e32 v4, 0xa00, v4
	v_lshlrev_b32_e32 v10, 16, v118
	v_and_b32_e32 v11, 0xffff0000, v118
	v_mul_f32_e32 v10, 0x3fb8aa3b, v10
	v_mul_f32_e32 v11, 0x3fb8aa3b, v11
	v_exp_f32_e32 v10, v10
	v_exp_f32_e32 v11, v11
	v_lshlrev_b32_e32 v12, 16, v134
	v_and_b32_e32 v13, 0xffff0000, v134
	v_pk_fma_f32 v[8:9], v[8:9], v[10:11], v[12:13]
	v_lshlrev_b32_e32 v14, 16, v150
	v_and_b32_e32 v15, 0xffff0000, v150
	v_mul_f32_e32 v14, v8, v14
	v_mul_f32_e32 v15, v9, v15
	v_cvt_pk_bf16_f32 v14, v14, v15
	global_store_dword v4, v14, s[22:23]
	v_add_u32_e32 v4, 0xa00, v4
	v_lshlrev_b32_e32 v10, 16, v119
	v_and_b32_e32 v11, 0xffff0000, v119
	v_mul_f32_e32 v10, 0x3fb8aa3b, v10
	v_mul_f32_e32 v11, 0x3fb8aa3b, v11
	v_exp_f32_e32 v10, v10
	v_exp_f32_e32 v11, v11
	v_lshlrev_b32_e32 v12, 16, v135
	v_and_b32_e32 v13, 0xffff0000, v135
	v_pk_fma_f32 v[8:9], v[8:9], v[10:11], v[12:13]
	v_lshlrev_b32_e32 v14, 16, v151
	v_and_b32_e32 v15, 0xffff0000, v151
	v_mul_f32_e32 v14, v8, v14
	v_mul_f32_e32 v15, v9, v15
	v_cvt_pk_bf16_f32 v14, v14, v15
	global_store_dword v4, v14, s[22:23]
	v_add_u32_e32 v4, 0xa00, v4
	v_lshlrev_b32_e32 v10, 16, v120
	v_and_b32_e32 v11, 0xffff0000, v120
	v_mul_f32_e32 v10, 0x3fb8aa3b, v10
	v_mul_f32_e32 v11, 0x3fb8aa3b, v11
	v_exp_f32_e32 v10, v10
	v_exp_f32_e32 v11, v11
	v_lshlrev_b32_e32 v12, 16, v136
	v_and_b32_e32 v13, 0xffff0000, v136
	v_pk_fma_f32 v[8:9], v[8:9], v[10:11], v[12:13]
	v_lshlrev_b32_e32 v14, 16, v152
	v_and_b32_e32 v15, 0xffff0000, v152
	v_mul_f32_e32 v14, v8, v14
	v_mul_f32_e32 v15, v9, v15
	v_cvt_pk_bf16_f32 v14, v14, v15
	global_store_dword v4, v14, s[22:23]
	v_add_u32_e32 v4, 0xa00, v4
	v_lshlrev_b32_e32 v10, 16, v121
	v_and_b32_e32 v11, 0xffff0000, v121
	v_mul_f32_e32 v10, 0x3fb8aa3b, v10
	v_mul_f32_e32 v11, 0x3fb8aa3b, v11
	v_exp_f32_e32 v10, v10
	v_exp_f32_e32 v11, v11
	v_lshlrev_b32_e32 v12, 16, v137
	v_and_b32_e32 v13, 0xffff0000, v137
	v_pk_fma_f32 v[8:9], v[8:9], v[10:11], v[12:13]
	v_lshlrev_b32_e32 v14, 16, v153
	v_and_b32_e32 v15, 0xffff0000, v153
	v_mul_f32_e32 v14, v8, v14
	v_mul_f32_e32 v15, v9, v15
	v_cvt_pk_bf16_f32 v14, v14, v15
	global_store_dword v4, v14, s[22:23]
	v_add_u32_e32 v4, 0xa00, v4
	v_lshlrev_b32_e32 v10, 16, v122
	v_and_b32_e32 v11, 0xffff0000, v122
	v_mul_f32_e32 v10, 0x3fb8aa3b, v10
	v_mul_f32_e32 v11, 0x3fb8aa3b, v11
	v_exp_f32_e32 v10, v10
	v_exp_f32_e32 v11, v11
	v_lshlrev_b32_e32 v12, 16, v138
	v_and_b32_e32 v13, 0xffff0000, v138
	v_pk_fma_f32 v[8:9], v[8:9], v[10:11], v[12:13]
	v_lshlrev_b32_e32 v14, 16, v154
	v_and_b32_e32 v15, 0xffff0000, v154
	v_mul_f32_e32 v14, v8, v14
	v_mul_f32_e32 v15, v9, v15
	v_cvt_pk_bf16_f32 v14, v14, v15
	global_store_dword v4, v14, s[22:23]
	v_add_u32_e32 v4, 0xa00, v4
	v_lshlrev_b32_e32 v10, 16, v123
	v_and_b32_e32 v11, 0xffff0000, v123
	v_mul_f32_e32 v10, 0x3fb8aa3b, v10
	v_mul_f32_e32 v11, 0x3fb8aa3b, v11
	v_exp_f32_e32 v10, v10
	v_exp_f32_e32 v11, v11
	v_lshlrev_b32_e32 v12, 16, v139
	v_and_b32_e32 v13, 0xffff0000, v139
	v_pk_fma_f32 v[8:9], v[8:9], v[10:11], v[12:13]
	v_lshlrev_b32_e32 v14, 16, v155
	v_and_b32_e32 v15, 0xffff0000, v155
	v_mul_f32_e32 v14, v8, v14
	v_mul_f32_e32 v15, v9, v15
	v_cvt_pk_bf16_f32 v14, v14, v15
	global_store_dword v4, v14, s[22:23]
	v_add_u32_e32 v4, 0xa00, v4
	s_waitcnt vmcnt(0)
	s_cmp_lt_u32 s3, 64
	s_cbranch_scc1 .Lsf_last32
	global_load_dword v108, v3, s[18:19]
	global_load_dword v124, v3, s[20:21]
	global_load_dword v140, v3, s[22:23]
	v_add_u32_e32 v3, 0xa00, v3
	global_load_dword v109, v3, s[18:19]
	global_load_dword v125, v3, s[20:21]
	global_load_dword v141, v3, s[22:23]
	v_add_u32_e32 v3, 0xa00, v3
	global_load_dword v110, v3, s[18:19]
	global_load_dword v126, v3, s[20:21]
	global_load_dword v142, v3, s[22:23]
	v_add_u32_e32 v3, 0xa00, v3
	global_load_dword v111, v3, s[18:19]
	global_load_dword v127, v3, s[20:21]
	global_load_dword v143, v3, s[22:23]
	v_add_u32_e32 v3, 0xa00, v3
	global_load_dword v112, v3, s[18:19]
	global_load_dword v128, v3, s[20:21]
	global_load_dword v144, v3, s[22:23]
	v_add_u32_e32 v3, 0xa00, v3
	global_load_dword v113, v3, s[18:19]
	global_load_dword v129, v3, s[20:21]
	global_load_dword v145, v3, s[22:23]
	v_add_u32_e32 v3, 0xa00, v3
	global_load_dword v114, v3, s[18:19]
	global_load_dword v130, v3, s[20:21]
	global_load_dword v146, v3, s[22:23]
	v_add_u32_e32 v3, 0xa00, v3
	global_load_dword v115, v3, s[18:19]
	global_load_dword v131, v3, s[20:21]
	global_load_dword v147, v3, s[22:23]
	v_add_u32_e32 v3, 0xa00, v3
	global_load_dword v116, v3, s[18:19]
	global_load_dword v132, v3, s[20:21]
	global_load_dword v148, v3, s[22:23]
	v_add_u32_e32 v3, 0xa00, v3
	global_load_dword v117, v3, s[18:19]
	global_load_dword v133, v3, s[20:21]
	global_load_dword v149, v3, s[22:23]
	v_add_u32_e32 v3, 0xa00, v3
	global_load_dword v118, v3, s[18:19]
	global_load_dword v134, v3, s[20:21]
	global_load_dword v150, v3, s[22:23]
	v_add_u32_e32 v3, 0xa00, v3
	global_load_dword v119, v3, s[18:19]
	global_load_dword v135, v3, s[20:21]
	global_load_dword v151, v3, s[22:23]
	v_add_u32_e32 v3, 0xa00, v3
	global_load_dword v120, v3, s[18:19]
	global_load_dword v136, v3, s[20:21]
	global_load_dword v152, v3, s[22:23]
	v_add_u32_e32 v3, 0xa00, v3
	global_load_dword v121, v3, s[18:19]
	global_load_dword v137, v3, s[20:21]
	global_load_dword v153, v3, s[22:23]
	v_add_u32_e32 v3, 0xa00, v3
	global_load_dword v122, v3, s[18:19]
	global_load_dword v138, v3, s[20:21]
	global_load_dword v154, v3, s[22:23]
	v_add_u32_e32 v3, 0xa00, v3
	global_load_dword v123, v3, s[18:19]
	global_load_dword v139, v3, s[20:21]
	global_load_dword v155, v3, s[22:23]
	v_add_u32_e32 v3, 0xa00, v3
	v_lshlrev_b32_e32 v10, 16, v44
	v_and_b32_e32 v11, 0xffff0000, v44
	v_mul_f32_e32 v10, 0x3fb8aa3b, v10
	v_mul_f32_e32 v11, 0x3fb8aa3b, v11
	v_exp_f32_e32 v10, v10
	v_exp_f32_e32 v11, v11
	v_lshlrev_b32_e32 v12, 16, v60
	v_and_b32_e32 v13, 0xffff0000, v60
	v_pk_fma_f32 v[8:9], v[8:9], v[10:11], v[12:13]
	v_lshlrev_b32_e32 v14, 16, v76
	v_and_b32_e32 v15, 0xffff0000, v76
	v_mul_f32_e32 v14, v8, v14
	v_mul_f32_e32 v15, v9, v15
	v_cvt_pk_bf16_f32 v14, v14, v15
	global_store_dword v4, v14, s[22:23]
	v_add_u32_e32 v4, 0xa00, v4
	v_lshlrev_b32_e32 v10, 16, v45
	v_and_b32_e32 v11, 0xffff0000, v45
	v_mul_f32_e32 v10, 0x3fb8aa3b, v10
	v_mul_f32_e32 v11, 0x3fb8aa3b, v11
	v_exp_f32_e32 v10, v10
	v_exp_f32_e32 v11, v11
	v_lshlrev_b32_e32 v12, 16, v61
	v_and_b32_e32 v13, 0xffff0000, v61
	v_pk_fma_f32 v[8:9], v[8:9], v[10:11], v[12:13]
	v_lshlrev_b32_e32 v14, 16, v77
	v_and_b32_e32 v15, 0xffff0000, v77
	v_mul_f32_e32 v14, v8, v14
	v_mul_f32_e32 v15, v9, v15
	v_cvt_pk_bf16_f32 v14, v14, v15
	global_store_dword v4, v14, s[22:23]
	v_add_u32_e32 v4, 0xa00, v4
	v_lshlrev_b32_e32 v10, 16, v46
	v_and_b32_e32 v11, 0xffff0000, v46
	v_mul_f32_e32 v10, 0x3fb8aa3b, v10
	v_mul_f32_e32 v11, 0x3fb8aa3b, v11
	v_exp_f32_e32 v10, v10
	v_exp_f32_e32 v11, v11
	v_lshlrev_b32_e32 v12, 16, v62
	v_and_b32_e32 v13, 0xffff0000, v62
	v_pk_fma_f32 v[8:9], v[8:9], v[10:11], v[12:13]
	v_lshlrev_b32_e32 v14, 16, v78
	v_and_b32_e32 v15, 0xffff0000, v78
	v_mul_f32_e32 v14, v8, v14
	v_mul_f32_e32 v15, v9, v15
	v_cvt_pk_bf16_f32 v14, v14, v15
	global_store_dword v4, v14, s[22:23]
	v_add_u32_e32 v4, 0xa00, v4
	v_lshlrev_b32_e32 v10, 16, v47
	v_and_b32_e32 v11, 0xffff0000, v47
	v_mul_f32_e32 v10, 0x3fb8aa3b, v10
	v_mul_f32_e32 v11, 0x3fb8aa3b, v11
	v_exp_f32_e32 v10, v10
	v_exp_f32_e32 v11, v11
	v_lshlrev_b32_e32 v12, 16, v63
	v_and_b32_e32 v13, 0xffff0000, v63
	v_pk_fma_f32 v[8:9], v[8:9], v[10:11], v[12:13]
	v_lshlrev_b32_e32 v14, 16, v79
	v_and_b32_e32 v15, 0xffff0000, v79
	v_mul_f32_e32 v14, v8, v14
	v_mul_f32_e32 v15, v9, v15
	v_cvt_pk_bf16_f32 v14, v14, v15
	global_store_dword v4, v14, s[22:23]
	v_add_u32_e32 v4, 0xa00, v4
	v_lshlrev_b32_e32 v10, 16, v48
	v_and_b32_e32 v11, 0xffff0000, v48
	v_mul_f32_e32 v10, 0x3fb8aa3b, v10
	v_mul_f32_e32 v11, 0x3fb8aa3b, v11
	v_exp_f32_e32 v10, v10
	v_exp_f32_e32 v11, v11
	v_lshlrev_b32_e32 v12, 16, v64
	v_and_b32_e32 v13, 0xffff0000, v64
	v_pk_fma_f32 v[8:9], v[8:9], v[10:11], v[12:13]
	v_lshlrev_b32_e32 v14, 16, v80
	v_and_b32_e32 v15, 0xffff0000, v80
	v_mul_f32_e32 v14, v8, v14
	v_mul_f32_e32 v15, v9, v15
	v_cvt_pk_bf16_f32 v14, v14, v15
	global_store_dword v4, v14, s[22:23]
	v_add_u32_e32 v4, 0xa00, v4
	v_lshlrev_b32_e32 v10, 16, v49
	v_and_b32_e32 v11, 0xffff0000, v49
	v_mul_f32_e32 v10, 0x3fb8aa3b, v10
	v_mul_f32_e32 v11, 0x3fb8aa3b, v11
	v_exp_f32_e32 v10, v10
	v_exp_f32_e32 v11, v11
	v_lshlrev_b32_e32 v12, 16, v65
	v_and_b32_e32 v13, 0xffff0000, v65
	v_pk_fma_f32 v[8:9], v[8:9], v[10:11], v[12:13]
	v_lshlrev_b32_e32 v14, 16, v81
	v_and_b32_e32 v15, 0xffff0000, v81
	v_mul_f32_e32 v14, v8, v14
	v_mul_f32_e32 v15, v9, v15
	v_cvt_pk_bf16_f32 v14, v14, v15
	global_store_dword v4, v14, s[22:23]
	v_add_u32_e32 v4, 0xa00, v4
	v_lshlrev_b32_e32 v10, 16, v50
	v_and_b32_e32 v11, 0xffff0000, v50
	v_mul_f32_e32 v10, 0x3fb8aa3b, v10
	v_mul_f32_e32 v11, 0x3fb8aa3b, v11
	v_exp_f32_e32 v10, v10
	v_exp_f32_e32 v11, v11
	v_lshlrev_b32_e32 v12, 16, v66
	v_and_b32_e32 v13, 0xffff0000, v66
	v_pk_fma_f32 v[8:9], v[8:9], v[10:11], v[12:13]
	v_lshlrev_b32_e32 v14, 16, v82
	v_and_b32_e32 v15, 0xffff0000, v82
	v_mul_f32_e32 v14, v8, v14
	v_mul_f32_e32 v15, v9, v15
	v_cvt_pk_bf16_f32 v14, v14, v15
	global_store_dword v4, v14, s[22:23]
	v_add_u32_e32 v4, 0xa00, v4
	v_lshlrev_b32_e32 v10, 16, v51
	v_and_b32_e32 v11, 0xffff0000, v51
	v_mul_f32_e32 v10, 0x3fb8aa3b, v10
	v_mul_f32_e32 v11, 0x3fb8aa3b, v11
	v_exp_f32_e32 v10, v10
	v_exp_f32_e32 v11, v11
	v_lshlrev_b32_e32 v12, 16, v67
	v_and_b32_e32 v13, 0xffff0000, v67
	v_pk_fma_f32 v[8:9], v[8:9], v[10:11], v[12:13]
	v_lshlrev_b32_e32 v14, 16, v83
	v_and_b32_e32 v15, 0xffff0000, v83
	v_mul_f32_e32 v14, v8, v14
	v_mul_f32_e32 v15, v9, v15
	v_cvt_pk_bf16_f32 v14, v14, v15
	global_store_dword v4, v14, s[22:23]
	v_add_u32_e32 v4, 0xa00, v4
	v_lshlrev_b32_e32 v10, 16, v52
	v_and_b32_e32 v11, 0xffff0000, v52
	v_mul_f32_e32 v10, 0x3fb8aa3b, v10
	v_mul_f32_e32 v11, 0x3fb8aa3b, v11
	v_exp_f32_e32 v10, v10
	v_exp_f32_e32 v11, v11
	v_lshlrev_b32_e32 v12, 16, v68
	v_and_b32_e32 v13, 0xffff0000, v68
	v_pk_fma_f32 v[8:9], v[8:9], v[10:11], v[12:13]
	v_lshlrev_b32_e32 v14, 16, v84
	v_and_b32_e32 v15, 0xffff0000, v84
	v_mul_f32_e32 v14, v8, v14
	v_mul_f32_e32 v15, v9, v15
	v_cvt_pk_bf16_f32 v14, v14, v15
	global_store_dword v4, v14, s[22:23]
	v_add_u32_e32 v4, 0xa00, v4
	v_lshlrev_b32_e32 v10, 16, v53
	v_and_b32_e32 v11, 0xffff0000, v53
	v_mul_f32_e32 v10, 0x3fb8aa3b, v10
	v_mul_f32_e32 v11, 0x3fb8aa3b, v11
	v_exp_f32_e32 v10, v10
	v_exp_f32_e32 v11, v11
	v_lshlrev_b32_e32 v12, 16, v69
	v_and_b32_e32 v13, 0xffff0000, v69
	v_pk_fma_f32 v[8:9], v[8:9], v[10:11], v[12:13]
	v_lshlrev_b32_e32 v14, 16, v85
	v_and_b32_e32 v15, 0xffff0000, v85
	v_mul_f32_e32 v14, v8, v14
	v_mul_f32_e32 v15, v9, v15
	v_cvt_pk_bf16_f32 v14, v14, v15
	global_store_dword v4, v14, s[22:23]
	v_add_u32_e32 v4, 0xa00, v4
	v_lshlrev_b32_e32 v10, 16, v54
	v_and_b32_e32 v11, 0xffff0000, v54
	v_mul_f32_e32 v10, 0x3fb8aa3b, v10
	v_mul_f32_e32 v11, 0x3fb8aa3b, v11
	v_exp_f32_e32 v10, v10
	v_exp_f32_e32 v11, v11
	v_lshlrev_b32_e32 v12, 16, v70
	v_and_b32_e32 v13, 0xffff0000, v70
	v_pk_fma_f32 v[8:9], v[8:9], v[10:11], v[12:13]
	v_lshlrev_b32_e32 v14, 16, v86
	v_and_b32_e32 v15, 0xffff0000, v86
	v_mul_f32_e32 v14, v8, v14
	v_mul_f32_e32 v15, v9, v15
	v_cvt_pk_bf16_f32 v14, v14, v15
	global_store_dword v4, v14, s[22:23]
	v_add_u32_e32 v4, 0xa00, v4
	v_lshlrev_b32_e32 v10, 16, v55
	v_and_b32_e32 v11, 0xffff0000, v55
	v_mul_f32_e32 v10, 0x3fb8aa3b, v10
	v_mul_f32_e32 v11, 0x3fb8aa3b, v11
	v_exp_f32_e32 v10, v10
	v_exp_f32_e32 v11, v11
	v_lshlrev_b32_e32 v12, 16, v71
	v_and_b32_e32 v13, 0xffff0000, v71
	v_pk_fma_f32 v[8:9], v[8:9], v[10:11], v[12:13]
	v_lshlrev_b32_e32 v14, 16, v87
	v_and_b32_e32 v15, 0xffff0000, v87
	v_mul_f32_e32 v14, v8, v14
	v_mul_f32_e32 v15, v9, v15
	v_cvt_pk_bf16_f32 v14, v14, v15
	global_store_dword v4, v14, s[22:23]
	v_add_u32_e32 v4, 0xa00, v4
	v_lshlrev_b32_e32 v10, 16, v56
	v_and_b32_e32 v11, 0xffff0000, v56
	v_mul_f32_e32 v10, 0x3fb8aa3b, v10
	v_mul_f32_e32 v11, 0x3fb8aa3b, v11
	v_exp_f32_e32 v10, v10
	v_exp_f32_e32 v11, v11
	v_lshlrev_b32_e32 v12, 16, v72
	v_and_b32_e32 v13, 0xffff0000, v72
	v_pk_fma_f32 v[8:9], v[8:9], v[10:11], v[12:13]
	v_lshlrev_b32_e32 v14, 16, v88
	v_and_b32_e32 v15, 0xffff0000, v88
	v_mul_f32_e32 v14, v8, v14
	v_mul_f32_e32 v15, v9, v15
	v_cvt_pk_bf16_f32 v14, v14, v15
	global_store_dword v4, v14, s[22:23]
	v_add_u32_e32 v4, 0xa00, v4
	v_lshlrev_b32_e32 v10, 16, v57
	v_and_b32_e32 v11, 0xffff0000, v57
	v_mul_f32_e32 v10, 0x3fb8aa3b, v10
	v_mul_f32_e32 v11, 0x3fb8aa3b, v11
	v_exp_f32_e32 v10, v10
	v_exp_f32_e32 v11, v11
	v_lshlrev_b32_e32 v12, 16, v73
	v_and_b32_e32 v13, 0xffff0000, v73
	v_pk_fma_f32 v[8:9], v[8:9], v[10:11], v[12:13]
	v_lshlrev_b32_e32 v14, 16, v89
	v_and_b32_e32 v15, 0xffff0000, v89
	v_mul_f32_e32 v14, v8, v14
	v_mul_f32_e32 v15, v9, v15
	v_cvt_pk_bf16_f32 v14, v14, v15
	global_store_dword v4, v14, s[22:23]
	v_add_u32_e32 v4, 0xa00, v4
	v_lshlrev_b32_e32 v10, 16, v58
	v_and_b32_e32 v11, 0xffff0000, v58
	v_mul_f32_e32 v10, 0x3fb8aa3b, v10
	v_mul_f32_e32 v11, 0x3fb8aa3b, v11
	v_exp_f32_e32 v10, v10
	v_exp_f32_e32 v11, v11
	v_lshlrev_b32_e32 v12, 16, v74
	v_and_b32_e32 v13, 0xffff0000, v74
	v_pk_fma_f32 v[8:9], v[8:9], v[10:11], v[12:13]
	v_lshlrev_b32_e32 v14, 16, v90
	v_and_b32_e32 v15, 0xffff0000, v90
	v_mul_f32_e32 v14, v8, v14
	v_mul_f32_e32 v15, v9, v15
	v_cvt_pk_bf16_f32 v14, v14, v15
	global_store_dword v4, v14, s[22:23]
	v_add_u32_e32 v4, 0xa00, v4
	v_lshlrev_b32_e32 v10, 16, v59
	v_and_b32_e32 v11, 0xffff0000, v59
	v_mul_f32_e32 v10, 0x3fb8aa3b, v10
	v_mul_f32_e32 v11, 0x3fb8aa3b, v11
	v_exp_f32_e32 v10, v10
	v_exp_f32_e32 v11, v11
	v_lshlrev_b32_e32 v12, 16, v75
	v_and_b32_e32 v13, 0xffff0000, v75
	v_pk_fma_f32 v[8:9], v[8:9], v[10:11], v[12:13]
	v_lshlrev_b32_e32 v14, 16, v91
	v_and_b32_e32 v15, 0xffff0000, v91
	v_mul_f32_e32 v14, v8, v14
	v_mul_f32_e32 v15, v9, v15
	v_cvt_pk_bf16_f32 v14, v14, v15
	global_store_dword v4, v14, s[22:23]
	v_add_u32_e32 v4, 0xa00, v4
	s_waitcnt vmcnt(0)
	global_load_dword v44, v3, s[18:19]
	global_load_dword v60, v3, s[20:21]
	global_load_dword v76, v3, s[22:23]
	v_add_u32_e32 v3, 0xa00, v3
	global_load_dword v45, v3, s[18:19]
	global_load_dword v61, v3, s[20:21]
	global_load_dword v77, v3, s[22:23]
	v_add_u32_e32 v3, 0xa00, v3
	global_load_dword v46, v3, s[18:19]
	global_load_dword v62, v3, s[20:21]
	global_load_dword v78, v3, s[22:23]
	v_add_u32_e32 v3, 0xa00, v3
	global_load_dword v47, v3, s[18:19]
	global_load_dword v63, v3, s[20:21]
	global_load_dword v79, v3, s[22:23]
	v_add_u32_e32 v3, 0xa00, v3
	global_load_dword v48, v3, s[18:19]
	global_load_dword v64, v3, s[20:21]
	global_load_dword v80, v3, s[22:23]
	v_add_u32_e32 v3, 0xa00, v3
	global_load_dword v49, v3, s[18:19]
	global_load_dword v65, v3, s[20:21]
	global_load_dword v81, v3, s[22:23]
	v_add_u32_e32 v3, 0xa00, v3
	global_load_dword v50, v3, s[18:19]
	global_load_dword v66, v3, s[20:21]
	global_load_dword v82, v3, s[22:23]
	v_add_u32_e32 v3, 0xa00, v3
	global_load_dword v51, v3, s[18:19]
	global_load_dword v67, v3, s[20:21]
	global_load_dword v83, v3, s[22:23]
	v_add_u32_e32 v3, 0xa00, v3
	global_load_dword v52, v3, s[18:19]
	global_load_dword v68, v3, s[20:21]
	global_load_dword v84, v3, s[22:23]
	v_add_u32_e32 v3, 0xa00, v3
	global_load_dword v53, v3, s[18:19]
	global_load_dword v69, v3, s[20:21]
	global_load_dword v85, v3, s[22:23]
	v_add_u32_e32 v3, 0xa00, v3
	global_load_dword v54, v3, s[18:19]
	global_load_dword v70, v3, s[20:21]
	global_load_dword v86, v3, s[22:23]
	v_add_u32_e32 v3, 0xa00, v3
	global_load_dword v55, v3, s[18:19]
	global_load_dword v71, v3, s[20:21]
	global_load_dword v87, v3, s[22:23]
	v_add_u32_e32 v3, 0xa00, v3
	global_load_dword v56, v3, s[18:19]
	global_load_dword v72, v3, s[20:21]
	global_load_dword v88, v3, s[22:23]
	v_add_u32_e32 v3, 0xa00, v3
	global_load_dword v57, v3, s[18:19]
	global_load_dword v73, v3, s[20:21]
	global_load_dword v89, v3, s[22:23]
	v_add_u32_e32 v3, 0xa00, v3
	global_load_dword v58, v3, s[18:19]
	global_load_dword v74, v3, s[20:21]
	global_load_dword v90, v3, s[22:23]
	v_add_u32_e32 v3, 0xa00, v3
	global_load_dword v59, v3, s[18:19]
	global_load_dword v75, v3, s[20:21]
	global_load_dword v91, v3, s[22:23]
	v_add_u32_e32 v3, 0xa00, v3
	v_lshlrev_b32_e32 v10, 16, v108
	v_and_b32_e32 v11, 0xffff0000, v108
	v_mul_f32_e32 v10, 0x3fb8aa3b, v10
	v_mul_f32_e32 v11, 0x3fb8aa3b, v11
	v_exp_f32_e32 v10, v10
	v_exp_f32_e32 v11, v11
	v_lshlrev_b32_e32 v12, 16, v124
	v_and_b32_e32 v13, 0xffff0000, v124
	v_pk_fma_f32 v[8:9], v[8:9], v[10:11], v[12:13]
	v_lshlrev_b32_e32 v14, 16, v140
	v_and_b32_e32 v15, 0xffff0000, v140
	v_mul_f32_e32 v14, v8, v14
	v_mul_f32_e32 v15, v9, v15
	v_cvt_pk_bf16_f32 v14, v14, v15
	global_store_dword v4, v14, s[22:23]
	v_add_u32_e32 v4, 0xa00, v4
	v_lshlrev_b32_e32 v10, 16, v109
	v_and_b32_e32 v11, 0xffff0000, v109
	v_mul_f32_e32 v10, 0x3fb8aa3b, v10
	v_mul_f32_e32 v11, 0x3fb8aa3b, v11
	v_exp_f32_e32 v10, v10
	v_exp_f32_e32 v11, v11
	v_lshlrev_b32_e32 v12, 16, v125
	v_and_b32_e32 v13, 0xffff0000, v125
	v_pk_fma_f32 v[8:9], v[8:9], v[10:11], v[12:13]
	v_lshlrev_b32_e32 v14, 16, v141
	v_and_b32_e32 v15, 0xffff0000, v141
	v_mul_f32_e32 v14, v8, v14
	v_mul_f32_e32 v15, v9, v15
	v_cvt_pk_bf16_f32 v14, v14, v15
	global_store_dword v4, v14, s[22:23]
	v_add_u32_e32 v4, 0xa00, v4
	v_lshlrev_b32_e32 v10, 16, v110
	v_and_b32_e32 v11, 0xffff0000, v110
	v_mul_f32_e32 v10, 0x3fb8aa3b, v10
	v_mul_f32_e32 v11, 0x3fb8aa3b, v11
	v_exp_f32_e32 v10, v10
	v_exp_f32_e32 v11, v11
	v_lshlrev_b32_e32 v12, 16, v126
	v_and_b32_e32 v13, 0xffff0000, v126
	v_pk_fma_f32 v[8:9], v[8:9], v[10:11], v[12:13]
	v_lshlrev_b32_e32 v14, 16, v142
	v_and_b32_e32 v15, 0xffff0000, v142
	v_mul_f32_e32 v14, v8, v14
	v_mul_f32_e32 v15, v9, v15
	v_cvt_pk_bf16_f32 v14, v14, v15
	global_store_dword v4, v14, s[22:23]
	v_add_u32_e32 v4, 0xa00, v4
	v_lshlrev_b32_e32 v10, 16, v111
	v_and_b32_e32 v11, 0xffff0000, v111
	v_mul_f32_e32 v10, 0x3fb8aa3b, v10
	v_mul_f32_e32 v11, 0x3fb8aa3b, v11
	v_exp_f32_e32 v10, v10
	v_exp_f32_e32 v11, v11
	v_lshlrev_b32_e32 v12, 16, v127
	v_and_b32_e32 v13, 0xffff0000, v127
	v_pk_fma_f32 v[8:9], v[8:9], v[10:11], v[12:13]
	v_lshlrev_b32_e32 v14, 16, v143
	v_and_b32_e32 v15, 0xffff0000, v143
	v_mul_f32_e32 v14, v8, v14
	v_mul_f32_e32 v15, v9, v15
	v_cvt_pk_bf16_f32 v14, v14, v15
	global_store_dword v4, v14, s[22:23]
	v_add_u32_e32 v4, 0xa00, v4
	v_lshlrev_b32_e32 v10, 16, v112
	v_and_b32_e32 v11, 0xffff0000, v112
	v_mul_f32_e32 v10, 0x3fb8aa3b, v10
	v_mul_f32_e32 v11, 0x3fb8aa3b, v11
	v_exp_f32_e32 v10, v10
	v_exp_f32_e32 v11, v11
	v_lshlrev_b32_e32 v12, 16, v128
	v_and_b32_e32 v13, 0xffff0000, v128
	v_pk_fma_f32 v[8:9], v[8:9], v[10:11], v[12:13]
	v_lshlrev_b32_e32 v14, 16, v144
	v_and_b32_e32 v15, 0xffff0000, v144
	v_mul_f32_e32 v14, v8, v14
	v_mul_f32_e32 v15, v9, v15
	v_cvt_pk_bf16_f32 v14, v14, v15
	global_store_dword v4, v14, s[22:23]
	v_add_u32_e32 v4, 0xa00, v4
	v_lshlrev_b32_e32 v10, 16, v113
	v_and_b32_e32 v11, 0xffff0000, v113
	v_mul_f32_e32 v10, 0x3fb8aa3b, v10
	v_mul_f32_e32 v11, 0x3fb8aa3b, v11
	v_exp_f32_e32 v10, v10
	v_exp_f32_e32 v11, v11
	v_lshlrev_b32_e32 v12, 16, v129
	v_and_b32_e32 v13, 0xffff0000, v129
	v_pk_fma_f32 v[8:9], v[8:9], v[10:11], v[12:13]
	v_lshlrev_b32_e32 v14, 16, v145
	v_and_b32_e32 v15, 0xffff0000, v145
	v_mul_f32_e32 v14, v8, v14
	v_mul_f32_e32 v15, v9, v15
	v_cvt_pk_bf16_f32 v14, v14, v15
	global_store_dword v4, v14, s[22:23]
	v_add_u32_e32 v4, 0xa00, v4
	v_lshlrev_b32_e32 v10, 16, v114
	v_and_b32_e32 v11, 0xffff0000, v114
	v_mul_f32_e32 v10, 0x3fb8aa3b, v10
	v_mul_f32_e32 v11, 0x3fb8aa3b, v11
	v_exp_f32_e32 v10, v10
	v_exp_f32_e32 v11, v11
	v_lshlrev_b32_e32 v12, 16, v130
	v_and_b32_e32 v13, 0xffff0000, v130
	v_pk_fma_f32 v[8:9], v[8:9], v[10:11], v[12:13]
	v_lshlrev_b32_e32 v14, 16, v146
	v_and_b32_e32 v15, 0xffff0000, v146
	v_mul_f32_e32 v14, v8, v14
	v_mul_f32_e32 v15, v9, v15
	v_cvt_pk_bf16_f32 v14, v14, v15
	global_store_dword v4, v14, s[22:23]
	v_add_u32_e32 v4, 0xa00, v4
	v_lshlrev_b32_e32 v10, 16, v115
	v_and_b32_e32 v11, 0xffff0000, v115
	v_mul_f32_e32 v10, 0x3fb8aa3b, v10
	v_mul_f32_e32 v11, 0x3fb8aa3b, v11
	v_exp_f32_e32 v10, v10
	v_exp_f32_e32 v11, v11
	v_lshlrev_b32_e32 v12, 16, v131
	v_and_b32_e32 v13, 0xffff0000, v131
	v_pk_fma_f32 v[8:9], v[8:9], v[10:11], v[12:13]
	v_lshlrev_b32_e32 v14, 16, v147
	v_and_b32_e32 v15, 0xffff0000, v147
	v_mul_f32_e32 v14, v8, v14
	v_mul_f32_e32 v15, v9, v15
	v_cvt_pk_bf16_f32 v14, v14, v15
	global_store_dword v4, v14, s[22:23]
	v_add_u32_e32 v4, 0xa00, v4
	v_lshlrev_b32_e32 v10, 16, v116
	v_and_b32_e32 v11, 0xffff0000, v116
	v_mul_f32_e32 v10, 0x3fb8aa3b, v10
	v_mul_f32_e32 v11, 0x3fb8aa3b, v11
	v_exp_f32_e32 v10, v10
	v_exp_f32_e32 v11, v11
	v_lshlrev_b32_e32 v12, 16, v132
	v_and_b32_e32 v13, 0xffff0000, v132
	v_pk_fma_f32 v[8:9], v[8:9], v[10:11], v[12:13]
	v_lshlrev_b32_e32 v14, 16, v148
	v_and_b32_e32 v15, 0xffff0000, v148
	v_mul_f32_e32 v14, v8, v14
	v_mul_f32_e32 v15, v9, v15
	v_cvt_pk_bf16_f32 v14, v14, v15
	global_store_dword v4, v14, s[22:23]
	v_add_u32_e32 v4, 0xa00, v4
	v_lshlrev_b32_e32 v10, 16, v117
	v_and_b32_e32 v11, 0xffff0000, v117
	v_mul_f32_e32 v10, 0x3fb8aa3b, v10
	v_mul_f32_e32 v11, 0x3fb8aa3b, v11
	v_exp_f32_e32 v10, v10
	v_exp_f32_e32 v11, v11
	v_lshlrev_b32_e32 v12, 16, v133
	v_and_b32_e32 v13, 0xffff0000, v133
	v_pk_fma_f32 v[8:9], v[8:9], v[10:11], v[12:13]
	v_lshlrev_b32_e32 v14, 16, v149
	v_and_b32_e32 v15, 0xffff0000, v149
	v_mul_f32_e32 v14, v8, v14
	v_mul_f32_e32 v15, v9, v15
	v_cvt_pk_bf16_f32 v14, v14, v15
	global_store_dword v4, v14, s[22:23]
	v_add_u32_e32 v4, 0xa00, v4
	v_lshlrev_b32_e32 v10, 16, v118
	v_and_b32_e32 v11, 0xffff0000, v118
	v_mul_f32_e32 v10, 0x3fb8aa3b, v10
	v_mul_f32_e32 v11, 0x3fb8aa3b, v11
	v_exp_f32_e32 v10, v10
	v_exp_f32_e32 v11, v11
	v_lshlrev_b32_e32 v12, 16, v134
	v_and_b32_e32 v13, 0xffff0000, v134
	v_pk_fma_f32 v[8:9], v[8:9], v[10:11], v[12:13]
	v_lshlrev_b32_e32 v14, 16, v150
	v_and_b32_e32 v15, 0xffff0000, v150
	v_mul_f32_e32 v14, v8, v14
	v_mul_f32_e32 v15, v9, v15
	v_cvt_pk_bf16_f32 v14, v14, v15
	global_store_dword v4, v14, s[22:23]
	v_add_u32_e32 v4, 0xa00, v4
	v_lshlrev_b32_e32 v10, 16, v119
	v_and_b32_e32 v11, 0xffff0000, v119
	v_mul_f32_e32 v10, 0x3fb8aa3b, v10
	v_mul_f32_e32 v11, 0x3fb8aa3b, v11
	v_exp_f32_e32 v10, v10
	v_exp_f32_e32 v11, v11
	v_lshlrev_b32_e32 v12, 16, v135
	v_and_b32_e32 v13, 0xffff0000, v135
	v_pk_fma_f32 v[8:9], v[8:9], v[10:11], v[12:13]
	v_lshlrev_b32_e32 v14, 16, v151
	v_and_b32_e32 v15, 0xffff0000, v151
	v_mul_f32_e32 v14, v8, v14
	v_mul_f32_e32 v15, v9, v15
	v_cvt_pk_bf16_f32 v14, v14, v15
	global_store_dword v4, v14, s[22:23]
	v_add_u32_e32 v4, 0xa00, v4
	v_lshlrev_b32_e32 v10, 16, v120
	v_and_b32_e32 v11, 0xffff0000, v120
	v_mul_f32_e32 v10, 0x3fb8aa3b, v10
	v_mul_f32_e32 v11, 0x3fb8aa3b, v11
	v_exp_f32_e32 v10, v10
	v_exp_f32_e32 v11, v11
	v_lshlrev_b32_e32 v12, 16, v136
	v_and_b32_e32 v13, 0xffff0000, v136
	v_pk_fma_f32 v[8:9], v[8:9], v[10:11], v[12:13]
	v_lshlrev_b32_e32 v14, 16, v152
	v_and_b32_e32 v15, 0xffff0000, v152
	v_mul_f32_e32 v14, v8, v14
	v_mul_f32_e32 v15, v9, v15
	v_cvt_pk_bf16_f32 v14, v14, v15
	global_store_dword v4, v14, s[22:23]
	v_add_u32_e32 v4, 0xa00, v4
	v_lshlrev_b32_e32 v10, 16, v121
	v_and_b32_e32 v11, 0xffff0000, v121
	v_mul_f32_e32 v10, 0x3fb8aa3b, v10
	v_mul_f32_e32 v11, 0x3fb8aa3b, v11
	v_exp_f32_e32 v10, v10
	v_exp_f32_e32 v11, v11
	v_lshlrev_b32_e32 v12, 16, v137
	v_and_b32_e32 v13, 0xffff0000, v137
	v_pk_fma_f32 v[8:9], v[8:9], v[10:11], v[12:13]
	v_lshlrev_b32_e32 v14, 16, v153
	v_and_b32_e32 v15, 0xffff0000, v153
	v_mul_f32_e32 v14, v8, v14
	v_mul_f32_e32 v15, v9, v15
	v_cvt_pk_bf16_f32 v14, v14, v15
	global_store_dword v4, v14, s[22:23]
	v_add_u32_e32 v4, 0xa00, v4
	v_lshlrev_b32_e32 v10, 16, v122
	v_and_b32_e32 v11, 0xffff0000, v122
	v_mul_f32_e32 v10, 0x3fb8aa3b, v10
	v_mul_f32_e32 v11, 0x3fb8aa3b, v11
	v_exp_f32_e32 v10, v10
	v_exp_f32_e32 v11, v11
	v_lshlrev_b32_e32 v12, 16, v138
	v_and_b32_e32 v13, 0xffff0000, v138
	v_pk_fma_f32 v[8:9], v[8:9], v[10:11], v[12:13]
	v_lshlrev_b32_e32 v14, 16, v154
	v_and_b32_e32 v15, 0xffff0000, v154
	v_mul_f32_e32 v14, v8, v14
	v_mul_f32_e32 v15, v9, v15
	v_cvt_pk_bf16_f32 v14, v14, v15
	global_store_dword v4, v14, s[22:23]
	v_add_u32_e32 v4, 0xa00, v4
	v_lshlrev_b32_e32 v10, 16, v123
	v_and_b32_e32 v11, 0xffff0000, v123
	v_mul_f32_e32 v10, 0x3fb8aa3b, v10
	v_mul_f32_e32 v11, 0x3fb8aa3b, v11
	v_exp_f32_e32 v10, v10
	v_exp_f32_e32 v11, v11
	v_lshlrev_b32_e32 v12, 16, v139
	v_and_b32_e32 v13, 0xffff0000, v139
	v_pk_fma_f32 v[8:9], v[8:9], v[10:11], v[12:13]
	v_lshlrev_b32_e32 v14, 16, v155
	v_and_b32_e32 v15, 0xffff0000, v155
	v_mul_f32_e32 v14, v8, v14
	v_mul_f32_e32 v15, v9, v15
	v_cvt_pk_bf16_f32 v14, v14, v15
	global_store_dword v4, v14, s[22:23]
	v_add_u32_e32 v4, 0xa00, v4
	s_waitcnt vmcnt(0)
	v_lshlrev_b32_e32 v10, 16, v44
	v_and_b32_e32 v11, 0xffff0000, v44
	v_mul_f32_e32 v10, 0x3fb8aa3b, v10
	v_mul_f32_e32 v11, 0x3fb8aa3b, v11
	v_exp_f32_e32 v10, v10
	v_exp_f32_e32 v11, v11
	v_lshlrev_b32_e32 v12, 16, v60
	v_and_b32_e32 v13, 0xffff0000, v60
	v_pk_fma_f32 v[8:9], v[8:9], v[10:11], v[12:13]
	v_lshlrev_b32_e32 v14, 16, v76
	v_and_b32_e32 v15, 0xffff0000, v76
	v_mul_f32_e32 v14, v8, v14
	v_mul_f32_e32 v15, v9, v15
	v_cvt_pk_bf16_f32 v14, v14, v15
	global_store_dword v4, v14, s[22:23]
	v_add_u32_e32 v4, 0xa00, v4
	v_lshlrev_b32_e32 v10, 16, v45
	v_and_b32_e32 v11, 0xffff0000, v45
	v_mul_f32_e32 v10, 0x3fb8aa3b, v10
	v_mul_f32_e32 v11, 0x3fb8aa3b, v11
	v_exp_f32_e32 v10, v10
	v_exp_f32_e32 v11, v11
	v_lshlrev_b32_e32 v12, 16, v61
	v_and_b32_e32 v13, 0xffff0000, v61
	v_pk_fma_f32 v[8:9], v[8:9], v[10:11], v[12:13]
	v_lshlrev_b32_e32 v14, 16, v77
	v_and_b32_e32 v15, 0xffff0000, v77
	v_mul_f32_e32 v14, v8, v14
	v_mul_f32_e32 v15, v9, v15
	v_cvt_pk_bf16_f32 v14, v14, v15
	global_store_dword v4, v14, s[22:23]
	v_add_u32_e32 v4, 0xa00, v4
	v_lshlrev_b32_e32 v10, 16, v46
	v_and_b32_e32 v11, 0xffff0000, v46
	v_mul_f32_e32 v10, 0x3fb8aa3b, v10
	v_mul_f32_e32 v11, 0x3fb8aa3b, v11
	v_exp_f32_e32 v10, v10
	v_exp_f32_e32 v11, v11
	v_lshlrev_b32_e32 v12, 16, v62
	v_and_b32_e32 v13, 0xffff0000, v62
	v_pk_fma_f32 v[8:9], v[8:9], v[10:11], v[12:13]
	v_lshlrev_b32_e32 v14, 16, v78
	v_and_b32_e32 v15, 0xffff0000, v78
	v_mul_f32_e32 v14, v8, v14
	v_mul_f32_e32 v15, v9, v15
	v_cvt_pk_bf16_f32 v14, v14, v15
	global_store_dword v4, v14, s[22:23]
	v_add_u32_e32 v4, 0xa00, v4
	v_lshlrev_b32_e32 v10, 16, v47
	v_and_b32_e32 v11, 0xffff0000, v47
	v_mul_f32_e32 v10, 0x3fb8aa3b, v10
	v_mul_f32_e32 v11, 0x3fb8aa3b, v11
	v_exp_f32_e32 v10, v10
	v_exp_f32_e32 v11, v11
	v_lshlrev_b32_e32 v12, 16, v63
	v_and_b32_e32 v13, 0xffff0000, v63
	v_pk_fma_f32 v[8:9], v[8:9], v[10:11], v[12:13]
	v_lshlrev_b32_e32 v14, 16, v79
	v_and_b32_e32 v15, 0xffff0000, v79
	v_mul_f32_e32 v14, v8, v14
	v_mul_f32_e32 v15, v9, v15
	v_cvt_pk_bf16_f32 v14, v14, v15
	global_store_dword v4, v14, s[22:23]
	v_add_u32_e32 v4, 0xa00, v4
	v_lshlrev_b32_e32 v10, 16, v48
	v_and_b32_e32 v11, 0xffff0000, v48
	v_mul_f32_e32 v10, 0x3fb8aa3b, v10
	v_mul_f32_e32 v11, 0x3fb8aa3b, v11
	v_exp_f32_e32 v10, v10
	v_exp_f32_e32 v11, v11
	v_lshlrev_b32_e32 v12, 16, v64
	v_and_b32_e32 v13, 0xffff0000, v64
	v_pk_fma_f32 v[8:9], v[8:9], v[10:11], v[12:13]
	v_lshlrev_b32_e32 v14, 16, v80
	v_and_b32_e32 v15, 0xffff0000, v80
	v_mul_f32_e32 v14, v8, v14
	v_mul_f32_e32 v15, v9, v15
	v_cvt_pk_bf16_f32 v14, v14, v15
	global_store_dword v4, v14, s[22:23]
	v_add_u32_e32 v4, 0xa00, v4
	v_lshlrev_b32_e32 v10, 16, v49
	v_and_b32_e32 v11, 0xffff0000, v49
	v_mul_f32_e32 v10, 0x3fb8aa3b, v10
	v_mul_f32_e32 v11, 0x3fb8aa3b, v11
	v_exp_f32_e32 v10, v10
	v_exp_f32_e32 v11, v11
	v_lshlrev_b32_e32 v12, 16, v65
	v_and_b32_e32 v13, 0xffff0000, v65
	v_pk_fma_f32 v[8:9], v[8:9], v[10:11], v[12:13]
	v_lshlrev_b32_e32 v14, 16, v81
	v_and_b32_e32 v15, 0xffff0000, v81
	v_mul_f32_e32 v14, v8, v14
	v_mul_f32_e32 v15, v9, v15
	v_cvt_pk_bf16_f32 v14, v14, v15
	global_store_dword v4, v14, s[22:23]
	v_add_u32_e32 v4, 0xa00, v4
	v_lshlrev_b32_e32 v10, 16, v50
	v_and_b32_e32 v11, 0xffff0000, v50
	v_mul_f32_e32 v10, 0x3fb8aa3b, v10
	v_mul_f32_e32 v11, 0x3fb8aa3b, v11
	v_exp_f32_e32 v10, v10
	v_exp_f32_e32 v11, v11
	v_lshlrev_b32_e32 v12, 16, v66
	v_and_b32_e32 v13, 0xffff0000, v66
	v_pk_fma_f32 v[8:9], v[8:9], v[10:11], v[12:13]
	v_lshlrev_b32_e32 v14, 16, v82
	v_and_b32_e32 v15, 0xffff0000, v82
	v_mul_f32_e32 v14, v8, v14
	v_mul_f32_e32 v15, v9, v15
	v_cvt_pk_bf16_f32 v14, v14, v15
	global_store_dword v4, v14, s[22:23]
	v_add_u32_e32 v4, 0xa00, v4
	v_lshlrev_b32_e32 v10, 16, v51
	v_and_b32_e32 v11, 0xffff0000, v51
	v_mul_f32_e32 v10, 0x3fb8aa3b, v10
	v_mul_f32_e32 v11, 0x3fb8aa3b, v11
	v_exp_f32_e32 v10, v10
	v_exp_f32_e32 v11, v11
	v_lshlrev_b32_e32 v12, 16, v67
	v_and_b32_e32 v13, 0xffff0000, v67
	v_pk_fma_f32 v[8:9], v[8:9], v[10:11], v[12:13]
	v_lshlrev_b32_e32 v14, 16, v83
	v_and_b32_e32 v15, 0xffff0000, v83
	v_mul_f32_e32 v14, v8, v14
	v_mul_f32_e32 v15, v9, v15
	v_cvt_pk_bf16_f32 v14, v14, v15
	global_store_dword v4, v14, s[22:23]
	v_add_u32_e32 v4, 0xa00, v4
	v_lshlrev_b32_e32 v10, 16, v52
	v_and_b32_e32 v11, 0xffff0000, v52
	v_mul_f32_e32 v10, 0x3fb8aa3b, v10
	v_mul_f32_e32 v11, 0x3fb8aa3b, v11
	v_exp_f32_e32 v10, v10
	v_exp_f32_e32 v11, v11
	v_lshlrev_b32_e32 v12, 16, v68
	v_and_b32_e32 v13, 0xffff0000, v68
	v_pk_fma_f32 v[8:9], v[8:9], v[10:11], v[12:13]
	v_lshlrev_b32_e32 v14, 16, v84
	v_and_b32_e32 v15, 0xffff0000, v84
	v_mul_f32_e32 v14, v8, v14
	v_mul_f32_e32 v15, v9, v15
	v_cvt_pk_bf16_f32 v14, v14, v15
	global_store_dword v4, v14, s[22:23]
	v_add_u32_e32 v4, 0xa00, v4
	v_lshlrev_b32_e32 v10, 16, v53
	v_and_b32_e32 v11, 0xffff0000, v53
	v_mul_f32_e32 v10, 0x3fb8aa3b, v10
	v_mul_f32_e32 v11, 0x3fb8aa3b, v11
	v_exp_f32_e32 v10, v10
	v_exp_f32_e32 v11, v11
	v_lshlrev_b32_e32 v12, 16, v69
	v_and_b32_e32 v13, 0xffff0000, v69
	v_pk_fma_f32 v[8:9], v[8:9], v[10:11], v[12:13]
	v_lshlrev_b32_e32 v14, 16, v85
	v_and_b32_e32 v15, 0xffff0000, v85
	v_mul_f32_e32 v14, v8, v14
	v_mul_f32_e32 v15, v9, v15
	v_cvt_pk_bf16_f32 v14, v14, v15
	global_store_dword v4, v14, s[22:23]
	v_add_u32_e32 v4, 0xa00, v4
	v_lshlrev_b32_e32 v10, 16, v54
	v_and_b32_e32 v11, 0xffff0000, v54
	v_mul_f32_e32 v10, 0x3fb8aa3b, v10
	v_mul_f32_e32 v11, 0x3fb8aa3b, v11
	v_exp_f32_e32 v10, v10
	v_exp_f32_e32 v11, v11
	v_lshlrev_b32_e32 v12, 16, v70
	v_and_b32_e32 v13, 0xffff0000, v70
	v_pk_fma_f32 v[8:9], v[8:9], v[10:11], v[12:13]
	v_lshlrev_b32_e32 v14, 16, v86
	v_and_b32_e32 v15, 0xffff0000, v86
	v_mul_f32_e32 v14, v8, v14
	v_mul_f32_e32 v15, v9, v15
	v_cvt_pk_bf16_f32 v14, v14, v15
	global_store_dword v4, v14, s[22:23]
	v_add_u32_e32 v4, 0xa00, v4
	v_lshlrev_b32_e32 v10, 16, v55
	v_and_b32_e32 v11, 0xffff0000, v55
	v_mul_f32_e32 v10, 0x3fb8aa3b, v10
	v_mul_f32_e32 v11, 0x3fb8aa3b, v11
	v_exp_f32_e32 v10, v10
	v_exp_f32_e32 v11, v11
	v_lshlrev_b32_e32 v12, 16, v71
	v_and_b32_e32 v13, 0xffff0000, v71
	v_pk_fma_f32 v[8:9], v[8:9], v[10:11], v[12:13]
	v_lshlrev_b32_e32 v14, 16, v87
	v_and_b32_e32 v15, 0xffff0000, v87
	v_mul_f32_e32 v14, v8, v14
	v_mul_f32_e32 v15, v9, v15
	v_cvt_pk_bf16_f32 v14, v14, v15
	global_store_dword v4, v14, s[22:23]
	v_add_u32_e32 v4, 0xa00, v4
	v_lshlrev_b32_e32 v10, 16, v56
	v_and_b32_e32 v11, 0xffff0000, v56
	v_mul_f32_e32 v10, 0x3fb8aa3b, v10
	v_mul_f32_e32 v11, 0x3fb8aa3b, v11
	v_exp_f32_e32 v10, v10
	v_exp_f32_e32 v11, v11
	v_lshlrev_b32_e32 v12, 16, v72
	v_and_b32_e32 v13, 0xffff0000, v72
	v_pk_fma_f32 v[8:9], v[8:9], v[10:11], v[12:13]
	v_lshlrev_b32_e32 v14, 16, v88
	v_and_b32_e32 v15, 0xffff0000, v88
	v_mul_f32_e32 v14, v8, v14
	v_mul_f32_e32 v15, v9, v15
	v_cvt_pk_bf16_f32 v14, v14, v15
	global_store_dword v4, v14, s[22:23]
	v_add_u32_e32 v4, 0xa00, v4
	v_lshlrev_b32_e32 v10, 16, v57
	v_and_b32_e32 v11, 0xffff0000, v57
	v_mul_f32_e32 v10, 0x3fb8aa3b, v10
	v_mul_f32_e32 v11, 0x3fb8aa3b, v11
	v_exp_f32_e32 v10, v10
	v_exp_f32_e32 v11, v11
	v_lshlrev_b32_e32 v12, 16, v73
	v_and_b32_e32 v13, 0xffff0000, v73
	v_pk_fma_f32 v[8:9], v[8:9], v[10:11], v[12:13]
	v_lshlrev_b32_e32 v14, 16, v89
	v_and_b32_e32 v15, 0xffff0000, v89
	v_mul_f32_e32 v14, v8, v14
	v_mul_f32_e32 v15, v9, v15
	v_cvt_pk_bf16_f32 v14, v14, v15
	global_store_dword v4, v14, s[22:23]
	v_add_u32_e32 v4, 0xa00, v4
	v_lshlrev_b32_e32 v10, 16, v58
	v_and_b32_e32 v11, 0xffff0000, v58
	v_mul_f32_e32 v10, 0x3fb8aa3b, v10
	v_mul_f32_e32 v11, 0x3fb8aa3b, v11
	v_exp_f32_e32 v10, v10
	v_exp_f32_e32 v11, v11
	v_lshlrev_b32_e32 v12, 16, v74
	v_and_b32_e32 v13, 0xffff0000, v74
	v_pk_fma_f32 v[8:9], v[8:9], v[10:11], v[12:13]
	v_lshlrev_b32_e32 v14, 16, v90
	v_and_b32_e32 v15, 0xffff0000, v90
	v_mul_f32_e32 v14, v8, v14
	v_mul_f32_e32 v15, v9, v15
	v_cvt_pk_bf16_f32 v14, v14, v15
	global_store_dword v4, v14, s[22:23]
	v_add_u32_e32 v4, 0xa00, v4
	v_lshlrev_b32_e32 v10, 16, v59
	v_and_b32_e32 v11, 0xffff0000, v59
	v_mul_f32_e32 v10, 0x3fb8aa3b, v10
	v_mul_f32_e32 v11, 0x3fb8aa3b, v11
	v_exp_f32_e32 v10, v10
	v_exp_f32_e32 v11, v11
	v_lshlrev_b32_e32 v12, 16, v75
	v_and_b32_e32 v13, 0xffff0000, v75
	v_pk_fma_f32 v[8:9], v[8:9], v[10:11], v[12:13]
	v_lshlrev_b32_e32 v14, 16, v91
	v_and_b32_e32 v15, 0xffff0000, v91
	v_mul_f32_e32 v14, v8, v14
	v_mul_f32_e32 v15, v9, v15
	v_cvt_pk_bf16_f32 v14, v14, v15
	global_store_dword v4, v14, s[22:23]
	v_add_u32_e32 v4, 0xa00, v4
	s_branch .LBB0_1006
.Lsf_last32:
	v_lshlrev_b32_e32 v10, 16, v44
	v_and_b32_e32 v11, 0xffff0000, v44
	v_mul_f32_e32 v10, 0x3fb8aa3b, v10
	v_mul_f32_e32 v11, 0x3fb8aa3b, v11
	v_exp_f32_e32 v10, v10
	v_exp_f32_e32 v11, v11
	v_lshlrev_b32_e32 v12, 16, v60
	v_and_b32_e32 v13, 0xffff0000, v60
	v_pk_fma_f32 v[8:9], v[8:9], v[10:11], v[12:13]
	v_lshlrev_b32_e32 v14, 16, v76
	v_and_b32_e32 v15, 0xffff0000, v76
	v_mul_f32_e32 v14, v8, v14
	v_mul_f32_e32 v15, v9, v15
	v_cvt_pk_bf16_f32 v14, v14, v15
	global_store_dword v4, v14, s[22:23]
	v_add_u32_e32 v4, 0xa00, v4
	v_lshlrev_b32_e32 v10, 16, v45
	v_and_b32_e32 v11, 0xffff0000, v45
	v_mul_f32_e32 v10, 0x3fb8aa3b, v10
	v_mul_f32_e32 v11, 0x3fb8aa3b, v11
	v_exp_f32_e32 v10, v10
	v_exp_f32_e32 v11, v11
	v_lshlrev_b32_e32 v12, 16, v61
	v_and_b32_e32 v13, 0xffff0000, v61
	v_pk_fma_f32 v[8:9], v[8:9], v[10:11], v[12:13]
	v_lshlrev_b32_e32 v14, 16, v77
	v_and_b32_e32 v15, 0xffff0000, v77
	v_mul_f32_e32 v14, v8, v14
	v_mul_f32_e32 v15, v9, v15
	v_cvt_pk_bf16_f32 v14, v14, v15
	global_store_dword v4, v14, s[22:23]
	v_add_u32_e32 v4, 0xa00, v4
	v_lshlrev_b32_e32 v10, 16, v46
	v_and_b32_e32 v11, 0xffff0000, v46
	v_mul_f32_e32 v10, 0x3fb8aa3b, v10
	v_mul_f32_e32 v11, 0x3fb8aa3b, v11
	v_exp_f32_e32 v10, v10
	v_exp_f32_e32 v11, v11
	v_lshlrev_b32_e32 v12, 16, v62
	v_and_b32_e32 v13, 0xffff0000, v62
	v_pk_fma_f32 v[8:9], v[8:9], v[10:11], v[12:13]
	v_lshlrev_b32_e32 v14, 16, v78
	v_and_b32_e32 v15, 0xffff0000, v78
	v_mul_f32_e32 v14, v8, v14
	v_mul_f32_e32 v15, v9, v15
	v_cvt_pk_bf16_f32 v14, v14, v15
	global_store_dword v4, v14, s[22:23]
	v_add_u32_e32 v4, 0xa00, v4
	v_lshlrev_b32_e32 v10, 16, v47
	v_and_b32_e32 v11, 0xffff0000, v47
	v_mul_f32_e32 v10, 0x3fb8aa3b, v10
	v_mul_f32_e32 v11, 0x3fb8aa3b, v11
	v_exp_f32_e32 v10, v10
	v_exp_f32_e32 v11, v11
	v_lshlrev_b32_e32 v12, 16, v63
	v_and_b32_e32 v13, 0xffff0000, v63
	v_pk_fma_f32 v[8:9], v[8:9], v[10:11], v[12:13]
	v_lshlrev_b32_e32 v14, 16, v79
	v_and_b32_e32 v15, 0xffff0000, v79
	v_mul_f32_e32 v14, v8, v14
	v_mul_f32_e32 v15, v9, v15
	v_cvt_pk_bf16_f32 v14, v14, v15
	global_store_dword v4, v14, s[22:23]
	v_add_u32_e32 v4, 0xa00, v4
	v_lshlrev_b32_e32 v10, 16, v48
	v_and_b32_e32 v11, 0xffff0000, v48
	v_mul_f32_e32 v10, 0x3fb8aa3b, v10
	v_mul_f32_e32 v11, 0x3fb8aa3b, v11
	v_exp_f32_e32 v10, v10
	v_exp_f32_e32 v11, v11
	v_lshlrev_b32_e32 v12, 16, v64
	v_and_b32_e32 v13, 0xffff0000, v64
	v_pk_fma_f32 v[8:9], v[8:9], v[10:11], v[12:13]
	v_lshlrev_b32_e32 v14, 16, v80
	v_and_b32_e32 v15, 0xffff0000, v80
	v_mul_f32_e32 v14, v8, v14
	v_mul_f32_e32 v15, v9, v15
	v_cvt_pk_bf16_f32 v14, v14, v15
	global_store_dword v4, v14, s[22:23]
	v_add_u32_e32 v4, 0xa00, v4
	v_lshlrev_b32_e32 v10, 16, v49
	v_and_b32_e32 v11, 0xffff0000, v49
	v_mul_f32_e32 v10, 0x3fb8aa3b, v10
	v_mul_f32_e32 v11, 0x3fb8aa3b, v11
	v_exp_f32_e32 v10, v10
	v_exp_f32_e32 v11, v11
	v_lshlrev_b32_e32 v12, 16, v65
	v_and_b32_e32 v13, 0xffff0000, v65
	v_pk_fma_f32 v[8:9], v[8:9], v[10:11], v[12:13]
	v_lshlrev_b32_e32 v14, 16, v81
	v_and_b32_e32 v15, 0xffff0000, v81
	v_mul_f32_e32 v14, v8, v14
	v_mul_f32_e32 v15, v9, v15
	v_cvt_pk_bf16_f32 v14, v14, v15
	global_store_dword v4, v14, s[22:23]
	v_add_u32_e32 v4, 0xa00, v4
	v_lshlrev_b32_e32 v10, 16, v50
	v_and_b32_e32 v11, 0xffff0000, v50
	v_mul_f32_e32 v10, 0x3fb8aa3b, v10
	v_mul_f32_e32 v11, 0x3fb8aa3b, v11
	v_exp_f32_e32 v10, v10
	v_exp_f32_e32 v11, v11
	v_lshlrev_b32_e32 v12, 16, v66
	v_and_b32_e32 v13, 0xffff0000, v66
	v_pk_fma_f32 v[8:9], v[8:9], v[10:11], v[12:13]
	v_lshlrev_b32_e32 v14, 16, v82
	v_and_b32_e32 v15, 0xffff0000, v82
	v_mul_f32_e32 v14, v8, v14
	v_mul_f32_e32 v15, v9, v15
	v_cvt_pk_bf16_f32 v14, v14, v15
	global_store_dword v4, v14, s[22:23]
	v_add_u32_e32 v4, 0xa00, v4
	v_lshlrev_b32_e32 v10, 16, v51
	v_and_b32_e32 v11, 0xffff0000, v51
	v_mul_f32_e32 v10, 0x3fb8aa3b, v10
	v_mul_f32_e32 v11, 0x3fb8aa3b, v11
	v_exp_f32_e32 v10, v10
	v_exp_f32_e32 v11, v11
	v_lshlrev_b32_e32 v12, 16, v67
	v_and_b32_e32 v13, 0xffff0000, v67
	v_pk_fma_f32 v[8:9], v[8:9], v[10:11], v[12:13]
	v_lshlrev_b32_e32 v14, 16, v83
	v_and_b32_e32 v15, 0xffff0000, v83
	v_mul_f32_e32 v14, v8, v14
	v_mul_f32_e32 v15, v9, v15
	v_cvt_pk_bf16_f32 v14, v14, v15
	global_store_dword v4, v14, s[22:23]
	v_add_u32_e32 v4, 0xa00, v4
	v_lshlrev_b32_e32 v10, 16, v52
	v_and_b32_e32 v11, 0xffff0000, v52
	v_mul_f32_e32 v10, 0x3fb8aa3b, v10
	v_mul_f32_e32 v11, 0x3fb8aa3b, v11
	v_exp_f32_e32 v10, v10
	v_exp_f32_e32 v11, v11
	v_lshlrev_b32_e32 v12, 16, v68
	v_and_b32_e32 v13, 0xffff0000, v68
	v_pk_fma_f32 v[8:9], v[8:9], v[10:11], v[12:13]
	v_lshlrev_b32_e32 v14, 16, v84
	v_and_b32_e32 v15, 0xffff0000, v84
	v_mul_f32_e32 v14, v8, v14
	v_mul_f32_e32 v15, v9, v15
	v_cvt_pk_bf16_f32 v14, v14, v15
	global_store_dword v4, v14, s[22:23]
	v_add_u32_e32 v4, 0xa00, v4
	v_lshlrev_b32_e32 v10, 16, v53
	v_and_b32_e32 v11, 0xffff0000, v53
	v_mul_f32_e32 v10, 0x3fb8aa3b, v10
	v_mul_f32_e32 v11, 0x3fb8aa3b, v11
	v_exp_f32_e32 v10, v10
	v_exp_f32_e32 v11, v11
	v_lshlrev_b32_e32 v12, 16, v69
	v_and_b32_e32 v13, 0xffff0000, v69
	v_pk_fma_f32 v[8:9], v[8:9], v[10:11], v[12:13]
	v_lshlrev_b32_e32 v14, 16, v85
	v_and_b32_e32 v15, 0xffff0000, v85
	v_mul_f32_e32 v14, v8, v14
	v_mul_f32_e32 v15, v9, v15
	v_cvt_pk_bf16_f32 v14, v14, v15
	global_store_dword v4, v14, s[22:23]
	v_add_u32_e32 v4, 0xa00, v4
	v_lshlrev_b32_e32 v10, 16, v54
	v_and_b32_e32 v11, 0xffff0000, v54
	v_mul_f32_e32 v10, 0x3fb8aa3b, v10
	v_mul_f32_e32 v11, 0x3fb8aa3b, v11
	v_exp_f32_e32 v10, v10
	v_exp_f32_e32 v11, v11
	v_lshlrev_b32_e32 v12, 16, v70
	v_and_b32_e32 v13, 0xffff0000, v70
	v_pk_fma_f32 v[8:9], v[8:9], v[10:11], v[12:13]
	v_lshlrev_b32_e32 v14, 16, v86
	v_and_b32_e32 v15, 0xffff0000, v86
	v_mul_f32_e32 v14, v8, v14
	v_mul_f32_e32 v15, v9, v15
	v_cvt_pk_bf16_f32 v14, v14, v15
	global_store_dword v4, v14, s[22:23]
	v_add_u32_e32 v4, 0xa00, v4
	v_lshlrev_b32_e32 v10, 16, v55
	v_and_b32_e32 v11, 0xffff0000, v55
	v_mul_f32_e32 v10, 0x3fb8aa3b, v10
	v_mul_f32_e32 v11, 0x3fb8aa3b, v11
	v_exp_f32_e32 v10, v10
	v_exp_f32_e32 v11, v11
	v_lshlrev_b32_e32 v12, 16, v71
	v_and_b32_e32 v13, 0xffff0000, v71
	v_pk_fma_f32 v[8:9], v[8:9], v[10:11], v[12:13]
	v_lshlrev_b32_e32 v14, 16, v87
	v_and_b32_e32 v15, 0xffff0000, v87
	v_mul_f32_e32 v14, v8, v14
	v_mul_f32_e32 v15, v9, v15
	v_cvt_pk_bf16_f32 v14, v14, v15
	global_store_dword v4, v14, s[22:23]
	v_add_u32_e32 v4, 0xa00, v4
	v_lshlrev_b32_e32 v10, 16, v56
	v_and_b32_e32 v11, 0xffff0000, v56
	v_mul_f32_e32 v10, 0x3fb8aa3b, v10
	v_mul_f32_e32 v11, 0x3fb8aa3b, v11
	v_exp_f32_e32 v10, v10
	v_exp_f32_e32 v11, v11
	v_lshlrev_b32_e32 v12, 16, v72
	v_and_b32_e32 v13, 0xffff0000, v72
	v_pk_fma_f32 v[8:9], v[8:9], v[10:11], v[12:13]
	v_lshlrev_b32_e32 v14, 16, v88
	v_and_b32_e32 v15, 0xffff0000, v88
	v_mul_f32_e32 v14, v8, v14
	v_mul_f32_e32 v15, v9, v15
	v_cvt_pk_bf16_f32 v14, v14, v15
	global_store_dword v4, v14, s[22:23]
	v_add_u32_e32 v4, 0xa00, v4
	v_lshlrev_b32_e32 v10, 16, v57
	v_and_b32_e32 v11, 0xffff0000, v57
	v_mul_f32_e32 v10, 0x3fb8aa3b, v10
	v_mul_f32_e32 v11, 0x3fb8aa3b, v11
	v_exp_f32_e32 v10, v10
	v_exp_f32_e32 v11, v11
	v_lshlrev_b32_e32 v12, 16, v73
	v_and_b32_e32 v13, 0xffff0000, v73
	v_pk_fma_f32 v[8:9], v[8:9], v[10:11], v[12:13]
	v_lshlrev_b32_e32 v14, 16, v89
	v_and_b32_e32 v15, 0xffff0000, v89
	v_mul_f32_e32 v14, v8, v14
	v_mul_f32_e32 v15, v9, v15
	v_cvt_pk_bf16_f32 v14, v14, v15
	global_store_dword v4, v14, s[22:23]
	v_add_u32_e32 v4, 0xa00, v4
	v_lshlrev_b32_e32 v10, 16, v58
	v_and_b32_e32 v11, 0xffff0000, v58
	v_mul_f32_e32 v10, 0x3fb8aa3b, v10
	v_mul_f32_e32 v11, 0x3fb8aa3b, v11
	v_exp_f32_e32 v10, v10
	v_exp_f32_e32 v11, v11
	v_lshlrev_b32_e32 v12, 16, v74
	v_and_b32_e32 v13, 0xffff0000, v74
	v_pk_fma_f32 v[8:9], v[8:9], v[10:11], v[12:13]
	v_lshlrev_b32_e32 v14, 16, v90
	v_and_b32_e32 v15, 0xffff0000, v90
	v_mul_f32_e32 v14, v8, v14
	v_mul_f32_e32 v15, v9, v15
	v_cvt_pk_bf16_f32 v14, v14, v15
	global_store_dword v4, v14, s[22:23]
	v_add_u32_e32 v4, 0xa00, v4
	v_lshlrev_b32_e32 v10, 16, v59
	v_and_b32_e32 v11, 0xffff0000, v59
	v_mul_f32_e32 v10, 0x3fb8aa3b, v10
	v_mul_f32_e32 v11, 0x3fb8aa3b, v11
	v_exp_f32_e32 v10, v10
	v_exp_f32_e32 v11, v11
	v_lshlrev_b32_e32 v12, 16, v75
	v_and_b32_e32 v13, 0xffff0000, v75
	v_pk_fma_f32 v[8:9], v[8:9], v[10:11], v[12:13]
	v_lshlrev_b32_e32 v14, 16, v91
	v_and_b32_e32 v15, 0xffff0000, v91
	v_mul_f32_e32 v14, v8, v14
	v_mul_f32_e32 v15, v9, v15
	v_cvt_pk_bf16_f32 v14, v14, v15
	global_store_dword v4, v14, s[22:23]
	v_add_u32_e32 v4, 0xa00, v4
	s_branch .LBB0_1006
